# loop-edge edit: K-loop counter SALU hoisted above the loop-back barrier and head address-select SALU sunk below the LDS fragment reads in the four GEMM K-loops
# speedup vs baseline: 1.0018x; 1.0018x over previous
; #define PG8_STAGE(bufoff, gbase, voff) do { _Pragma("unroll") for (int _i = 0; _i < 2; ++_i) \
;         __builtin_amdgcn_global_load_lds((const unsigned*)((const char*)(gbase) + (voff)[_i]), (LAS unsigned*)(lds + (bufoff) + ldsw + _i * 8192), 16, 0, 0); } while (0)
; #define PG8_LDA(dst, b, h) do { _Pragma("unroll") for (int m = 0; m < 4; ++m) _Pragma("unroll") for (int k = 0; k < 2; ++k) dst[m][k] = *(const LAS bf16x8*)(lds + PG8_SA(b, h) + aoff + m * 2048 + k * 1024); } while (0)
; #define PG8_LDB(dst, b, h) do { _Pragma("unroll") for (int n = 0; n < 2; ++n) _Pragma("unroll") for (int k = 0; k < 2; ++k) dst[n][k] = *(const LAS bf16x8*)(lds + PG8_SB(b, h) + boff + n * 2048 + k * 1024); } while (0)
; #define PG8_MMA(ai, bj, At, Bt) do { __builtin_amdgcn_s_setprio(1); _Pragma("unroll") for (int m = 0; m < 4; ++m) _Pragma("unroll") for (int n = 0; n < 2; ++n) _Pragma("unroll") for (int k = 0; k < 2; ++k) \
;         acc[ai][bj][m][n] = __builtin_amdgcn_mfma_f32_16x16x32_bf16(Bt[n][k], At[m][k], acc[ai][bj][m][n], 0, 0, 0); __builtin_amdgcn_s_setprio(0); } while (0)
; #define PG8_WAIT_V(n) asm volatile("s_waitcnt vmcnt(" #n ")" ::: "memory")
; #define PG8_WAIT_L(n) asm volatile("s_waitcnt lgkmcnt(" #n ")" ::: "memory")
; #define PG8_BAR __builtin_amdgcn_s_barrier()
; #define PG8_SCHED __builtin_amdgcn_sched_barrier(0)
; template <class Epi>
; __device__ __forceinline__ void gemm_phase(LAS unsigned char* lds, const Gemm g, const int G, const int cidx, const Epi& E) {
;     ...
;             const char* a1 = cA + (size_t)(t + 1) * kstep;
;             const char* a2 = last ? nA : cA + (size_t)(t + 2) * kstep; const char* b2 = last ? nB : cB + (size_t)(t + 2) * kstep;
;             const char* a3 = a2 + kstep; const char* b3 = b2 + kstep;
;             PG8_LDB(B0, 0, 0); PG8_LDB(B1, 0, 1); PG8_SCHED; PG8_LDA(At, 0, 0); PG8_STAGE(PG8_SA(1, 1), a1 + hstep, voffA);
;             PG8_WAIT_V(8); PG8_WAIT_L(0); PG8_BAR; PG8_MMA(0, 0, At, B0); PG8_MMA(0, 1, At, B1); PG8_BAR; PG8_SCHED;
;             PG8_LDA(At, 0, 1); PG8_STAGE(PG8_SB(0, 0), b2, voffB); PG8_STAGE(PG8_SB(0, 1), b2 + hstep, voffB); PG8_STAGE(PG8_SA(0, 0), a2, voffA);
.LBB0_82:
	s_add_i32 s43, 0, 0x10000
	s_add_i32 s68, 0, 0x14000
	v_add_u32_e32 v162, s43, v145
	v_add_u32_e32 v178, s68, v145
	ds_read_b128 v[132:135], v162
	ds_read_b128 v[140:143], v162 offset:1024
	ds_read_b128 v[156:159], v162 offset:2048
	ds_read_b128 v[162:165], v162 offset:3072
	ds_read_b128 v[166:169], v178
	ds_read_b128 v[170:173], v178 offset:1024
	ds_read_b128 v[174:177], v178 offset:2048
	ds_read_b128 v[178:181], v178 offset:3072
	v_lshl_add_u64 v[226:227], s[24:25], 0, v[154:155]
	s_add_i32 m0, s21, 0xc000
	ds_read_b128 v[182:185], v161
	ds_read_b128 v[186:189], v161 offset:1024
	ds_read_b128 v[190:193], v161 offset:2048
	ds_read_b128 v[194:197], v161 offset:3072
	ds_read_b128 v[198:201], v161 offset:4096
	ds_read_b128 v[214:217], v161 offset:5120
	ds_read_b128 v[218:221], v161 offset:6144
	ds_read_b128 v[222:225], v161 offset:7168
	s_add_u32 s26, s24, 0xfffc0080
	s_addc_u32 s27, s25, -1
	s_cmp_eq_u32 s45, 12
	s_cselect_b32 s29, s13, s27
	s_cselect_b32 s28, s17, s26
	s_cselect_b32 s27, s9, s44
	s_cselect_b32 s26, s22, s33
	global_load_lds_dwordx4 v[226:227], off
	v_lshl_add_u64 v[226:227], s[24:25], 0, v[152:153]
	s_add_i32 m0, s21, 0xe000
	s_nop 0
	global_load_lds_dwordx4 v[226:227], off
	s_waitcnt vmcnt(8)
	s_waitcnt lgkmcnt(0)
	s_barrier
	s_setprio 1
	s_waitcnt lgkmcnt(0)
	v_mfma_f32_16x16x32_bf16 v[128:131], v[132:135], v[182:185], v[128:131]
	v_mfma_f32_16x16x32_bf16 v[120:123], v[156:159], v[182:185], v[120:123]
	v_mfma_f32_16x16x32_bf16 v[112:115], v[132:135], v[190:193], v[112:115]
	v_mfma_f32_16x16x32_bf16 v[104:107], v[156:159], v[190:193], v[104:107]
	v_mfma_f32_16x16x32_bf16 v[96:99], v[132:135], v[198:201], v[96:99]
	v_mfma_f32_16x16x32_bf16 v[88:91], v[156:159], v[198:201], v[88:91]
	v_mfma_f32_16x16x32_bf16 v[80:83], v[132:135], v[218:221], v[80:83]
	v_mfma_f32_16x16x32_bf16 v[72:75], v[156:159], v[218:221], v[72:75]
	v_mfma_f32_16x16x32_bf16 v[128:131], v[140:143], v[186:189], v[128:131]
	v_mfma_f32_16x16x32_bf16 v[120:123], v[162:165], v[186:189], v[120:123]
	v_mfma_f32_16x16x32_bf16 v[112:115], v[140:143], v[194:197], v[112:115]
	v_mfma_f32_16x16x32_bf16 v[104:107], v[162:165], v[194:197], v[104:107]
	v_mfma_f32_16x16x32_bf16 v[96:99], v[140:143], v[214:217], v[96:99]
	v_mfma_f32_16x16x32_bf16 v[88:91], v[162:165], v[214:217], v[88:91]
	v_mfma_f32_16x16x32_bf16 v[80:83], v[140:143], v[222:225], v[80:83]
	v_mfma_f32_16x16x32_bf16 v[72:75], v[162:165], v[222:225], v[72:75]
	s_setprio 0
	s_setprio 1
	v_mfma_f32_16x16x32_bf16 v[124:127], v[166:169], v[182:185], v[124:127]
	v_mfma_f32_16x16x32_bf16 v[116:119], v[174:177], v[182:185], v[116:119]
	v_mfma_f32_16x16x32_bf16 v[108:111], v[166:169], v[190:193], v[108:111]
	v_mfma_f32_16x16x32_bf16 v[100:103], v[174:177], v[190:193], v[100:103]
	v_mfma_f32_16x16x32_bf16 v[92:95], v[166:169], v[198:201], v[92:95]
	v_mfma_f32_16x16x32_bf16 v[84:87], v[174:177], v[198:201], v[84:87]
	v_mfma_f32_16x16x32_bf16 v[76:79], v[166:169], v[218:221], v[76:79]
	v_mfma_f32_16x16x32_bf16 v[68:71], v[174:177], v[218:221], v[68:71]
	v_mfma_f32_16x16x32_bf16 v[124:127], v[170:173], v[186:189], v[124:127]
	v_mfma_f32_16x16x32_bf16 v[116:119], v[178:181], v[186:189], v[116:119]
	v_mfma_f32_16x16x32_bf16 v[108:111], v[170:173], v[194:197], v[108:111]
	v_mfma_f32_16x16x32_bf16 v[100:103], v[178:181], v[194:197], v[100:103]
	v_mfma_f32_16x16x32_bf16 v[92:95], v[170:173], v[214:217], v[92:95]
	v_mfma_f32_16x16x32_bf16 v[84:87], v[178:181], v[214:217], v[84:87]
	v_mfma_f32_16x16x32_bf16 v[76:79], v[170:173], v[222:225], v[76:79]
	v_mfma_f32_16x16x32_bf16 v[68:71], v[178:181], v[222:225], v[68:71]
	s_setprio 0
	s_barrier
	s_add_i32 s43, s43, s36
	v_lshl_add_u64 v[226:227], s[26:27], 0, v[148:149]
	s_mov_b32 m0, s43
	ds_read_b128 v[182:185], v161 offset:16384
	ds_read_b128 v[186:189], v161 offset:17408
	ds_read_b128 v[190:193], v161 offset:18432
	ds_read_b128 v[194:197], v161 offset:19456
	ds_read_b128 v[198:201], v161 offset:20480
	ds_read_b128 v[214:217], v161 offset:21504
	ds_read_b128 v[218:221], v161 offset:22528
	ds_read_b128 v[222:225], v161 offset:23552
	global_load_lds_dwordx4 v[226:227], off
	s_add_i32 m0, s43, 0x2000
	s_add_u32 s76, s26, 0x40000
	v_lshl_add_u64 v[228:229], s[26:27], 0, v[0:1]
	s_addc_u32 s77, s27, 0
	s_add_i32 s43, s68, s36
	global_load_lds_dwordx4 v[228:229], off
	v_lshl_add_u64 v[230:231], s[76:77], 0, v[148:149]
	s_mov_b32 m0, s43
	v_lshl_add_u64 v[232:233], s[28:29], 0, v[146:147]
	global_load_lds_dwordx4 v[230:231], off
	v_lshl_add_u64 v[230:231], s[76:77], 0, v[0:1]
	s_add_i32 m0, s43, 0x2000
	s_nop 0
	global_load_lds_dwordx4 v[230:231], off
	v_lshl_add_u64 v[230:231], s[28:29], 0, v[150:151]
	s_mov_b32 m0, s21
	s_nop 0
	global_load_lds_dwordx4 v[230:231], off
	s_mov_b32 m0, s38
	s_nop 0
	global_load_lds_dwordx4 v[232:233], off
	s_waitcnt vmcnt(8)
	s_waitcnt lgkmcnt(0)
	s_barrier
; #define PG8_STAGE(bufoff, gbase, voff) do { _Pragma("unroll") for (int _i = 0; _i < 2; ++_i) \
;         __builtin_amdgcn_global_load_lds((const unsigned*)((const char*)(gbase) + (voff)[_i]), (LAS unsigned*)(lds + (bufoff) + ldsw + _i * 8192), 16, 0, 0); } while (0)
; #define PG8_LDA(dst, b, h) do { _Pragma("unroll") for (int m = 0; m < 4; ++m) _Pragma("unroll") for (int k = 0; k < 2; ++k) dst[m][k] = *(const LAS bf16x8*)(lds + PG8_SA(b, h) + aoff + m * 2048 + k * 1024); } while (0)
; #define PG8_LDB(dst, b, h) do { _Pragma("unroll") for (int n = 0; n < 2; ++n) _Pragma("unroll") for (int k = 0; k < 2; ++k) dst[n][k] = *(const LAS bf16x8*)(lds + PG8_SB(b, h) + boff + n * 2048 + k * 1024); } while (0)
; #define PG8_MMA(ai, bj, At, Bt) do { __builtin_amdgcn_s_setprio(1); _Pragma("unroll") for (int m = 0; m < 4; ++m) _Pragma("unroll") for (int n = 0; n < 2; ++n) _Pragma("unroll") for (int k = 0; k < 2; ++k) \
;         acc[ai][bj][m][n] = __builtin_amdgcn_mfma_f32_16x16x32_bf16(Bt[n][k], At[m][k], acc[ai][bj][m][n], 0, 0, 0); __builtin_amdgcn_s_setprio(0); } while (0)
; #define PG8_WAIT_V(n) asm volatile("s_waitcnt vmcnt(" #n ")" ::: "memory")
; #define PG8_WAIT_L(n) asm volatile("s_waitcnt lgkmcnt(" #n ")" ::: "memory")
; #define PG8_BAR __builtin_amdgcn_s_barrier()
; #define PG8_SCHED __builtin_amdgcn_sched_barrier(0)
; template <class Epi>
; __device__ __forceinline__ void gemm_phase(LAS unsigned char* lds, const Gemm g, const int G, const int cidx, const Epi& E) {
;     ...
;             PG8_WAIT_V(8); PG8_WAIT_L(0); PG8_BAR; PG8_MMA(0, 0, At, B0); PG8_MMA(0, 1, At, B1); PG8_BAR; PG8_SCHED;
;             PG8_LDA(At, 0, 1); PG8_STAGE(PG8_SB(0, 0), b2, voffB); PG8_STAGE(PG8_SB(0, 1), b2 + hstep, voffB); PG8_STAGE(PG8_SA(0, 0), a2, voffA);
;             PG8_WAIT_V(8); PG8_WAIT_L(0); PG8_BAR; PG8_MMA(1, 0, At, B0); PG8_MMA(1, 1, At, B1); PG8_BAR; PG8_SCHED;
;             PG8_LDB(B0, 1, 0); PG8_LDB(B1, 1, 1); PG8_SCHED; PG8_LDA(At, 1, 0); PG8_STAGE(PG8_SA(0, 1), a2 + hstep, voffA);
;             PG8_WAIT_V(8); PG8_WAIT_L(0); PG8_BAR; PG8_MMA(0, 0, At, B0); PG8_MMA(0, 1, At, B1); PG8_BAR; PG8_SCHED;
;             PG8_LDA(At, 1, 1); PG8_STAGE(PG8_SB(1, 0), b3, voffB); PG8_STAGE(PG8_SB(1, 1), b3 + hstep, voffB); PG8_STAGE(PG8_SA(1, 0), a3, voffA);
;             PG8_WAIT_V(8); PG8_WAIT_L(0); PG8_BAR; PG8_MMA(1, 0, At, B0); PG8_MMA(1, 1, At, B1); PG8_BAR; PG8_SCHED;
	s_setprio 1
	s_waitcnt lgkmcnt(0)
	v_mfma_f32_16x16x32_bf16 v[64:67], v[132:135], v[182:185], v[64:67]
	v_mfma_f32_16x16x32_bf16 v[56:59], v[156:159], v[182:185], v[56:59]
	v_mfma_f32_16x16x32_bf16 v[48:51], v[132:135], v[190:193], v[48:51]
	v_mfma_f32_16x16x32_bf16 v[40:43], v[156:159], v[190:193], v[40:43]
	v_mfma_f32_16x16x32_bf16 v[32:35], v[132:135], v[198:201], v[32:35]
	v_mfma_f32_16x16x32_bf16 v[24:27], v[156:159], v[198:201], v[24:27]
	v_mfma_f32_16x16x32_bf16 v[16:19], v[132:135], v[218:221], v[16:19]
	v_mfma_f32_16x16x32_bf16 v[8:11], v[156:159], v[218:221], v[8:11]
	v_mfma_f32_16x16x32_bf16 v[64:67], v[140:143], v[186:189], v[64:67]
	v_mfma_f32_16x16x32_bf16 v[56:59], v[162:165], v[186:189], v[56:59]
	v_mfma_f32_16x16x32_bf16 v[48:51], v[140:143], v[194:197], v[48:51]
	v_mfma_f32_16x16x32_bf16 v[40:43], v[162:165], v[194:197], v[40:43]
	v_mfma_f32_16x16x32_bf16 v[32:35], v[140:143], v[214:217], v[32:35]
	v_mfma_f32_16x16x32_bf16 v[24:27], v[162:165], v[214:217], v[24:27]
	v_mfma_f32_16x16x32_bf16 v[16:19], v[140:143], v[222:225], v[16:19]
	v_mfma_f32_16x16x32_bf16 v[8:11], v[162:165], v[222:225], v[8:11]
	s_setprio 0
	s_setprio 1
	v_mfma_f32_16x16x32_bf16 v[60:63], v[166:169], v[182:185], v[60:63]
	v_mfma_f32_16x16x32_bf16 v[52:55], v[174:177], v[182:185], v[52:55]
	v_mfma_f32_16x16x32_bf16 v[44:47], v[166:169], v[190:193], v[44:47]
	v_mfma_f32_16x16x32_bf16 v[36:39], v[174:177], v[190:193], v[36:39]
	v_mfma_f32_16x16x32_bf16 v[28:31], v[166:169], v[198:201], v[28:31]
	v_mfma_f32_16x16x32_bf16 v[20:23], v[174:177], v[198:201], v[20:23]
	v_mfma_f32_16x16x32_bf16 v[12:15], v[166:169], v[218:221], v[12:15]
	v_mfma_f32_16x16x32_bf16 v[4:7], v[174:177], v[218:221], v[4:7]
	v_mfma_f32_16x16x32_bf16 v[60:63], v[170:173], v[186:189], v[60:63]
	v_mfma_f32_16x16x32_bf16 v[52:55], v[178:181], v[186:189], v[52:55]
	v_mfma_f32_16x16x32_bf16 v[44:47], v[170:173], v[194:197], v[44:47]
	v_mfma_f32_16x16x32_bf16 v[36:39], v[178:181], v[194:197], v[36:39]
	v_mfma_f32_16x16x32_bf16 v[28:31], v[170:173], v[214:217], v[28:31]
	v_mfma_f32_16x16x32_bf16 v[20:23], v[178:181], v[214:217], v[20:23]
	v_mfma_f32_16x16x32_bf16 v[12:15], v[170:173], v[222:225], v[12:15]
	v_mfma_f32_16x16x32_bf16 v[4:7], v[178:181], v[222:225], v[4:7]
	s_setprio 0
	s_barrier
	s_add_i32 s43, 0, 0x18000
	s_add_i32 s68, 0, 0x1c000
	v_add_u32_e32 v162, s43, v145
	v_add_u32_e32 v178, s68, v145
	ds_read_b128 v[132:135], v162
	ds_read_b128 v[140:143], v162 offset:1024
	ds_read_b128 v[156:159], v162 offset:2048
	ds_read_b128 v[162:165], v162 offset:3072
	ds_read_b128 v[166:169], v178
	ds_read_b128 v[170:173], v178 offset:1024
	ds_read_b128 v[174:177], v178 offset:2048
	ds_read_b128 v[178:181], v178 offset:3072
	s_add_u32 s28, s28, 0x40000
	s_addc_u32 s29, s29, 0
	s_mov_b32 m0, s39
	v_lshl_add_u64 v[234:235], s[28:29], 0, v[150:151]
	ds_read_b128 v[182:185], v161 offset:32768
	ds_read_b128 v[186:189], v161 offset:33792
	ds_read_b128 v[190:193], v161 offset:34816
	ds_read_b128 v[194:197], v161 offset:35840
	ds_read_b128 v[198:201], v161 offset:36864
	ds_read_b128 v[214:217], v161 offset:37888
	ds_read_b128 v[218:221], v161 offset:38912
	ds_read_b128 v[222:225], v161 offset:39936
	global_load_lds_dwordx4 v[234:235], off
	v_lshl_add_u64 v[234:235], s[28:29], 0, v[146:147]
	s_mov_b32 m0, s75
	s_nop 0
	global_load_lds_dwordx4 v[234:235], off
	s_waitcnt vmcnt(8)
	s_waitcnt lgkmcnt(0)
	s_barrier
	s_setprio 1
	s_waitcnt lgkmcnt(0)
	v_mfma_f32_16x16x32_bf16 v[128:131], v[132:135], v[182:185], v[128:131]
	v_mfma_f32_16x16x32_bf16 v[120:123], v[156:159], v[182:185], v[120:123]
	v_mfma_f32_16x16x32_bf16 v[112:115], v[132:135], v[190:193], v[112:115]
	v_mfma_f32_16x16x32_bf16 v[104:107], v[156:159], v[190:193], v[104:107]
	v_mfma_f32_16x16x32_bf16 v[96:99], v[132:135], v[198:201], v[96:99]
	v_mfma_f32_16x16x32_bf16 v[88:91], v[156:159], v[198:201], v[88:91]
	v_mfma_f32_16x16x32_bf16 v[80:83], v[132:135], v[218:221], v[80:83]
	v_mfma_f32_16x16x32_bf16 v[72:75], v[156:159], v[218:221], v[72:75]
	v_mfma_f32_16x16x32_bf16 v[128:131], v[140:143], v[186:189], v[128:131]
	v_mfma_f32_16x16x32_bf16 v[120:123], v[162:165], v[186:189], v[120:123]
	v_mfma_f32_16x16x32_bf16 v[112:115], v[140:143], v[194:197], v[112:115]
	v_mfma_f32_16x16x32_bf16 v[104:107], v[162:165], v[194:197], v[104:107]
	v_mfma_f32_16x16x32_bf16 v[96:99], v[140:143], v[214:217], v[96:99]
	v_mfma_f32_16x16x32_bf16 v[88:91], v[162:165], v[214:217], v[88:91]
	v_mfma_f32_16x16x32_bf16 v[80:83], v[140:143], v[222:225], v[80:83]
	v_mfma_f32_16x16x32_bf16 v[72:75], v[162:165], v[222:225], v[72:75]
	s_setprio 0
	s_setprio 1
	v_mfma_f32_16x16x32_bf16 v[124:127], v[166:169], v[182:185], v[124:127]
	v_mfma_f32_16x16x32_bf16 v[116:119], v[174:177], v[182:185], v[116:119]
	v_mfma_f32_16x16x32_bf16 v[108:111], v[166:169], v[190:193], v[108:111]
	v_mfma_f32_16x16x32_bf16 v[100:103], v[174:177], v[190:193], v[100:103]
	v_mfma_f32_16x16x32_bf16 v[92:95], v[166:169], v[198:201], v[92:95]
	v_mfma_f32_16x16x32_bf16 v[84:87], v[174:177], v[198:201], v[84:87]
	v_mfma_f32_16x16x32_bf16 v[76:79], v[166:169], v[218:221], v[76:79]
	v_mfma_f32_16x16x32_bf16 v[68:71], v[174:177], v[218:221], v[68:71]
	v_mfma_f32_16x16x32_bf16 v[124:127], v[170:173], v[186:189], v[124:127]
	v_mfma_f32_16x16x32_bf16 v[116:119], v[178:181], v[186:189], v[116:119]
	v_mfma_f32_16x16x32_bf16 v[108:111], v[170:173], v[194:197], v[108:111]
	v_mfma_f32_16x16x32_bf16 v[100:103], v[178:181], v[194:197], v[100:103]
	v_mfma_f32_16x16x32_bf16 v[92:95], v[170:173], v[214:217], v[92:95]
	v_mfma_f32_16x16x32_bf16 v[84:87], v[178:181], v[214:217], v[84:87]
	v_mfma_f32_16x16x32_bf16 v[76:79], v[170:173], v[222:225], v[76:79]
	v_mfma_f32_16x16x32_bf16 v[68:71], v[178:181], v[222:225], v[68:71]
	s_setprio 0
	s_barrier
; __device__ __forceinline__ unsigned pk2(float lo, float hi) { unsigned r; asm("v_cvt_pk_bf16_f32 %0, %1, %2" : "=v"(r) : "v"(lo), "v"(hi)); return r; }
; __device__ __forceinline__ float silu(float x) { return x * sigm(x); }
; #define PG8_STAGE(bufoff, gbase, voff) do { _Pragma("unroll") for (int _i = 0; _i < 2; ++_i) \
;         __builtin_amdgcn_global_load_lds((const unsigned*)((const char*)(gbase) + (voff)[_i]), (LAS unsigned*)(lds + (bufoff) + ldsw + _i * 8192), 16, 0, 0); } while (0)
; #define PG8_LDA(dst, b, h) do { _Pragma("unroll") for (int m = 0; m < 4; ++m) _Pragma("unroll") for (int k = 0; k < 2; ++k) dst[m][k] = *(const LAS bf16x8*)(lds + PG8_SA(b, h) + aoff + m * 2048 + k * 1024); } while (0)
; #define PG8_BAR __builtin_amdgcn_s_barrier()
;     __device__ __forceinline__ void operator()(const f32x4 (&acc)[2][2][4][2], const Unit& u, int wr, int wc, int fr, int fq) const {
;         const int row0 = u.pm * BM + wr * 64 + fr, col0 = u.pn * HALF + wc * 32 + 8 * fq;
; #pragma unroll
;         for (int ai = 0; ai < 2; ++ai)
; #pragma unroll
;             for (int m = 0; m < 4; ++m) { bf16_t* rowp = O + (size_t)(row0 + ai * HALF + m * 16) * ldc + col0;
;                 const f32x4 g0 = acc[ai][0][m][0], g1 = acc[ai][0][m][1], u0 = acc[ai][1][m][0], u1 = acc[ai][1][m][1];
;                 u32x4 w; w.x = pk2(silu(g0[0]) * u0[0], silu(g0[1]) * u0[1]); w.y = pk2(silu(g0[2]) * u0[2], silu(g0[3]) * u0[3]);
;                 w.z = pk2(silu(g1[0]) * u1[0], silu(g1[1]) * u1[1]); w.w = pk2(silu(g1[2]) * u1[2], silu(g1[3]) * u1[3]);
;                 *(u32x4*)rowp = w; }
; template <class Epi>
; __device__ __forceinline__ void gemm_phase(LAS unsigned char* lds, const Gemm g, const int G, const int cidx, const Epi& E) {
;     ...
;             PG8_WAIT_V(8); PG8_WAIT_L(0); PG8_BAR; PG8_MMA(1, 0, At, B0); PG8_MMA(1, 1, At, B1); PG8_BAR; PG8_SCHED;
;             PG8_LDB(B0, 1, 0); PG8_LDB(B1, 1, 1); PG8_SCHED; PG8_LDA(At, 1, 0); PG8_STAGE(PG8_SA(0, 1), a2 + hstep, voffA);
;             PG8_WAIT_V(8); PG8_WAIT_L(0); PG8_BAR; PG8_MMA(0, 0, At, B0); PG8_MMA(0, 1, At, B1); PG8_BAR; PG8_SCHED;
;             PG8_LDA(At, 1, 1); PG8_STAGE(PG8_SB(1, 0), b3, voffB); PG8_STAGE(PG8_SB(1, 1), b3 + hstep, voffB); PG8_STAGE(PG8_SA(1, 0), a3, voffA);
;             PG8_WAIT_V(8); PG8_WAIT_L(0); PG8_BAR; PG8_MMA(1, 0, At, B0); PG8_MMA(1, 1, At, B1); PG8_BAR; PG8_SCHED;
;         }
	s_add_i32 s28, s43, s36
	v_lshl_add_u64 v[226:227], v[226:227], 0, s[46:47]
	s_mov_b32 m0, s28
	ds_read_b128 v[182:185], v161 offset:49152
	ds_read_b128 v[186:189], v161 offset:50176
	ds_read_b128 v[190:193], v161 offset:51200
	ds_read_b128 v[194:197], v161 offset:52224
	ds_read_b128 v[198:201], v161 offset:53248
	ds_read_b128 v[214:217], v161 offset:54272
	ds_read_b128 v[218:221], v161 offset:55296
	ds_read_b128 v[222:225], v161 offset:56320
	global_load_lds_dwordx4 v[226:227], off
	s_add_i32 m0, s28, 0x2000
	s_add_u32 s26, s26, 0x40080
	v_lshl_add_u64 v[226:227], v[228:229], 0, s[46:47]
	s_addc_u32 s27, s27, 0
	s_add_i32 s28, s68, s36
	global_load_lds_dwordx4 v[226:227], off
	v_lshl_add_u64 v[226:227], s[26:27], 0, v[148:149]
	s_mov_b32 m0, s28
	s_nop 0
	global_load_lds_dwordx4 v[226:227], off
	v_lshl_add_u64 v[226:227], s[26:27], 0, v[0:1]
	s_add_i32 m0, s28, 0x2000
	s_nop 0
	global_load_lds_dwordx4 v[226:227], off
	v_lshl_add_u64 v[226:227], v[230:231], 0, s[46:47]
	s_mov_b32 m0, s79
	s_nop 0
	global_load_lds_dwordx4 v[226:227], off
	v_lshl_add_u64 v[226:227], v[232:233], 0, s[46:47]
	s_mov_b32 m0, s34
	s_nop 0
	global_load_lds_dwordx4 v[226:227], off
	s_waitcnt vmcnt(8)
	s_waitcnt lgkmcnt(0)
	s_barrier
	s_setprio 1
	s_waitcnt lgkmcnt(0)
	v_mfma_f32_16x16x32_bf16 v[64:67], v[132:135], v[182:185], v[64:67]
	v_mfma_f32_16x16x32_bf16 v[56:59], v[156:159], v[182:185], v[56:59]
	v_mfma_f32_16x16x32_bf16 v[48:51], v[132:135], v[190:193], v[48:51]
	v_mfma_f32_16x16x32_bf16 v[40:43], v[156:159], v[190:193], v[40:43]
	v_mfma_f32_16x16x32_bf16 v[32:35], v[132:135], v[198:201], v[32:35]
	v_mfma_f32_16x16x32_bf16 v[24:27], v[156:159], v[198:201], v[24:27]
	v_mfma_f32_16x16x32_bf16 v[16:19], v[132:135], v[218:221], v[16:19]
	v_mfma_f32_16x16x32_bf16 v[8:11], v[156:159], v[218:221], v[8:11]
	v_mfma_f32_16x16x32_bf16 v[64:67], v[140:143], v[186:189], v[64:67]
	v_mfma_f32_16x16x32_bf16 v[56:59], v[162:165], v[186:189], v[56:59]
	v_mfma_f32_16x16x32_bf16 v[48:51], v[140:143], v[194:197], v[48:51]
	v_mfma_f32_16x16x32_bf16 v[40:43], v[162:165], v[194:197], v[40:43]
	v_mfma_f32_16x16x32_bf16 v[32:35], v[140:143], v[214:217], v[32:35]
	v_mfma_f32_16x16x32_bf16 v[24:27], v[162:165], v[214:217], v[24:27]
	v_mfma_f32_16x16x32_bf16 v[16:19], v[140:143], v[222:225], v[16:19]
	v_mfma_f32_16x16x32_bf16 v[8:11], v[162:165], v[222:225], v[8:11]
	s_setprio 0
	s_setprio 1
	v_mfma_f32_16x16x32_bf16 v[60:63], v[166:169], v[182:185], v[60:63]
	v_mfma_f32_16x16x32_bf16 v[52:55], v[174:177], v[182:185], v[52:55]
	v_mfma_f32_16x16x32_bf16 v[44:47], v[166:169], v[190:193], v[44:47]
	v_mfma_f32_16x16x32_bf16 v[36:39], v[174:177], v[190:193], v[36:39]
	v_mfma_f32_16x16x32_bf16 v[28:31], v[166:169], v[198:201], v[28:31]
	v_mfma_f32_16x16x32_bf16 v[20:23], v[174:177], v[198:201], v[20:23]
	v_mfma_f32_16x16x32_bf16 v[12:15], v[166:169], v[218:221], v[12:15]
	v_mfma_f32_16x16x32_bf16 v[4:7], v[174:177], v[218:221], v[4:7]
	v_mfma_f32_16x16x32_bf16 v[60:63], v[170:173], v[186:189], v[60:63]
	v_mfma_f32_16x16x32_bf16 v[52:55], v[178:181], v[186:189], v[52:55]
	v_mfma_f32_16x16x32_bf16 v[44:47], v[170:173], v[194:197], v[44:47]
	v_mfma_f32_16x16x32_bf16 v[36:39], v[178:181], v[194:197], v[36:39]
	v_mfma_f32_16x16x32_bf16 v[28:31], v[170:173], v[214:217], v[28:31]
	v_mfma_f32_16x16x32_bf16 v[20:23], v[178:181], v[214:217], v[20:23]
	v_mfma_f32_16x16x32_bf16 v[12:15], v[170:173], v[222:225], v[12:15]
	v_mfma_f32_16x16x32_bf16 v[4:7], v[178:181], v[222:225], v[4:7]
	s_add_i32 s45, s45, 2
	s_add_u32 s33, s33, 0x100
	s_addc_u32 s44, s44, 0
	s_add_u32 s24, s24, 0x100
	s_addc_u32 s25, s25, 0
	s_cmp_gt_u32 s45, 13
	s_setprio 0
	s_barrier
	s_cbranch_scc0 .LBB0_82
	v_lshl_or_b32 v132, s16, 7, v160
	v_lshl_add_u32 v162, s20, 8, v3
	v_ashrrev_i32_e32 v133, 31, v132
	v_mov_b64_e32 v[156:157], s[6:7]
	s_movk_i32 s9, 0x1600
	v_mad_i64_i32 v[134:135], s[16:17], v162, s9, v[156:157]
	v_lshlrev_b64 v[158:159], 1, v[132:133]
	v_lshl_add_u64 v[132:133], v[134:135], 0, v[158:159]
	v_mul_f32_e32 v134, 0xbfb8aa3b, v128
	v_exp_f32_e32 v134, v134
	s_and_b64 vcc, exec, s[4:5]
	s_mov_b32 s20, s12
	s_mov_b64 s[24:25], s[18:19]
	v_add_f32_e32 v134, 1.0, v134
	v_rcp_f32_e32 v134, v134
	s_mov_b64 s[26:27], s[14:15]
	v_mul_f32_e32 v128, v128, v134
	v_mul_f32_e32 v124, v128, v124
	v_mul_f32_e32 v128, 0xbfb8aa3b, v129
	v_exp_f32_e32 v128, v128
	s_nop 0
	v_add_f32_e32 v128, 1.0, v128
	v_rcp_f32_e32 v128, v128
	s_nop 0
	v_mul_f32_e32 v128, v129, v128
	v_mul_f32_e32 v125, v128, v125
	v_cvt_pk_bf16_f32 v124, v124, v125
	v_mul_f32_e32 v125, 0xbfb8aa3b, v130
	v_exp_f32_e32 v125, v125
	s_nop 0
	v_add_f32_e32 v125, 1.0, v125
	v_rcp_f32_e32 v125, v125
	s_nop 0
	v_mul_f32_e32 v125, v130, v125
	v_mul_f32_e32 v125, v125, v126
	v_mul_f32_e32 v126, 0xbfb8aa3b, v131
	v_exp_f32_e32 v126, v126
	s_nop 0
	v_add_f32_e32 v126, 1.0, v126
	v_rcp_f32_e32 v126, v126
	s_nop 0
	v_mul_f32_e32 v126, v131, v126
	v_mul_f32_e32 v126, v126, v127
	v_cvt_pk_bf16_f32 v125, v125, v126
	v_mul_f32_e32 v126, 0xbfb8aa3b, v120
	v_exp_f32_e32 v126, v126
	s_nop 0
	v_add_f32_e32 v126, 1.0, v126
	v_rcp_f32_e32 v126, v126
	s_nop 0
	v_mul_f32_e32 v120, v120, v126
	v_mul_f32_e32 v116, v120, v116
	v_mul_f32_e32 v120, 0xbfb8aa3b, v121
	v_exp_f32_e32 v120, v120
	s_nop 0
	v_add_f32_e32 v120, 1.0, v120
	v_rcp_f32_e32 v120, v120
	s_nop 0
	v_mul_f32_e32 v120, v121, v120
	v_mul_f32_e32 v117, v120, v117
	v_cvt_pk_bf16_f32 v126, v116, v117
	v_mul_f32_e32 v116, 0xbfb8aa3b, v122
	v_exp_f32_e32 v116, v116
	v_mul_f32_e32 v117, 0xbfb8aa3b, v123
	v_exp_f32_e32 v117, v117
	v_add_f32_e32 v116, 1.0, v116
	v_rcp_f32_e32 v116, v116
	v_add_f32_e32 v117, 1.0, v117
	v_rcp_f32_e32 v117, v117
; __device__ __forceinline__ unsigned pk2(float lo, float hi) { unsigned r; asm("v_cvt_pk_bf16_f32 %0, %1, %2" : "=v"(r) : "v"(lo), "v"(hi)); return r; }
; __device__ __forceinline__ float silu(float x) { return x * sigm(x); }
;     __device__ __forceinline__ void operator()(const f32x4 (&acc)[2][2][4][2], const Unit& u, int wr, int wc, int fr, int fq) const {
;         const int row0 = u.pm * BM + wr * 64 + fr, col0 = u.pn * HALF + wc * 32 + 8 * fq;
; #pragma unroll
;         for (int ai = 0; ai < 2; ++ai)
; #pragma unroll
;             for (int m = 0; m < 4; ++m) { bf16_t* rowp = O + (size_t)(row0 + ai * HALF + m * 16) * ldc + col0;
;                 const f32x4 g0 = acc[ai][0][m][0], g1 = acc[ai][0][m][1], u0 = acc[ai][1][m][0], u1 = acc[ai][1][m][1];
;                 u32x4 w; w.x = pk2(silu(g0[0]) * u0[0], silu(g0[1]) * u0[1]); w.y = pk2(silu(g0[2]) * u0[2], silu(g0[3]) * u0[3]);
;                 w.z = pk2(silu(g1[0]) * u1[0], silu(g1[1]) * u1[1]); w.w = pk2(silu(g1[2]) * u1[2], silu(g1[3]) * u1[3]);
;                 *(u32x4*)rowp = w; }
	v_mul_f32_e32 v116, v122, v116
	v_mul_f32_e32 v116, v116, v118
	v_mul_f32_e32 v118, 0xbfb8aa3b, v112
	v_exp_f32_e32 v118, v118
	v_mul_f32_e32 v117, v123, v117
	v_mul_f32_e32 v117, v117, v119
	v_cvt_pk_bf16_f32 v127, v116, v117
	v_add_f32_e32 v118, 1.0, v118
	v_rcp_f32_e32 v118, v118
	s_mov_b64 s[98:99], 0x16000
	v_mul_f32_e32 v112, v112, v118
	v_mul_f32_e32 v108, v112, v108
	v_mul_f32_e32 v112, 0xbfb8aa3b, v113
	v_exp_f32_e32 v112, v112
	v_lshl_add_u64 v[116:117], v[132:133], 0, s[98:99]
	global_store_dwordx4 v[132:133], v[124:127], off
	v_add_f32_e32 v112, 1.0, v112
	v_rcp_f32_e32 v112, v112
	s_nop 0
	v_mul_f32_e32 v112, v113, v112
	v_mul_f32_e32 v109, v112, v109
	v_cvt_pk_bf16_f32 v108, v108, v109
	v_mul_f32_e32 v109, 0xbfb8aa3b, v114
	v_exp_f32_e32 v109, v109
	s_nop 0
	v_add_f32_e32 v109, 1.0, v109
	v_rcp_f32_e32 v109, v109
	s_nop 0
	v_mul_f32_e32 v109, v114, v109
	v_mul_f32_e32 v109, v109, v110
	v_mul_f32_e32 v110, 0xbfb8aa3b, v115
	v_exp_f32_e32 v110, v110
	s_nop 0
	v_add_f32_e32 v110, 1.0, v110
	v_rcp_f32_e32 v110, v110
	s_nop 0
	v_mul_f32_e32 v110, v115, v110
	v_mul_f32_e32 v110, v110, v111
	v_cvt_pk_bf16_f32 v109, v109, v110
	v_mul_f32_e32 v110, 0xbfb8aa3b, v104
	v_exp_f32_e32 v110, v110
	s_nop 0
	v_add_f32_e32 v110, 1.0, v110
	v_rcp_f32_e32 v110, v110
	s_nop 0
	v_mul_f32_e32 v104, v104, v110
	v_mul_f32_e32 v100, v104, v100
	v_mul_f32_e32 v104, 0xbfb8aa3b, v105
	v_exp_f32_e32 v104, v104
	s_nop 0
	v_add_f32_e32 v104, 1.0, v104
	v_rcp_f32_e32 v104, v104
	s_nop 0
	v_mul_f32_e32 v104, v105, v104
	v_mul_f32_e32 v101, v104, v101
	v_cvt_pk_bf16_f32 v110, v100, v101
	v_mul_f32_e32 v100, 0xbfb8aa3b, v106
	v_exp_f32_e32 v100, v100
	v_mul_f32_e32 v101, 0xbfb8aa3b, v107
	v_exp_f32_e32 v101, v101
	v_add_f32_e32 v100, 1.0, v100
	v_rcp_f32_e32 v100, v100
	v_add_f32_e32 v101, 1.0, v101
	v_rcp_f32_e32 v101, v101
	v_mul_f32_e32 v100, v106, v100
	v_mul_f32_e32 v100, v100, v102
	v_mul_f32_e32 v102, 0xbfb8aa3b, v96
	v_exp_f32_e32 v102, v102
	v_mul_f32_e32 v101, v107, v101
	v_mul_f32_e32 v101, v101, v103
	v_cvt_pk_bf16_f32 v111, v100, v101
	v_add_f32_e32 v102, 1.0, v102
	v_rcp_f32_e32 v102, v102
	s_mov_b64 s[98:99], 0x2c000
	v_mul_f32_e32 v96, v96, v102
	v_mul_f32_e32 v92, v96, v92
	v_mul_f32_e32 v96, 0xbfb8aa3b, v97
	v_exp_f32_e32 v96, v96
	v_lshl_add_u64 v[100:101], v[132:133], 0, s[98:99]
	global_store_dwordx4 v[116:117], v[108:111], off
	v_add_f32_e32 v96, 1.0, v96
	v_rcp_f32_e32 v96, v96
	s_nop 0
	v_mul_f32_e32 v96, v97, v96
	v_mul_f32_e32 v93, v96, v93
	v_cvt_pk_bf16_f32 v92, v92, v93
	v_mul_f32_e32 v93, 0xbfb8aa3b, v98
	v_exp_f32_e32 v93, v93
	s_nop 0
	v_add_f32_e32 v93, 1.0, v93
	v_rcp_f32_e32 v93, v93
	s_nop 0
	v_mul_f32_e32 v93, v98, v93
	v_mul_f32_e32 v93, v93, v94
	v_mul_f32_e32 v94, 0xbfb8aa3b, v99
	v_exp_f32_e32 v94, v94
	s_nop 0
	v_add_f32_e32 v94, 1.0, v94
	v_rcp_f32_e32 v94, v94
	s_nop 0
	v_mul_f32_e32 v94, v99, v94
	v_mul_f32_e32 v94, v94, v95
	v_cvt_pk_bf16_f32 v93, v93, v94
	v_mul_f32_e32 v94, 0xbfb8aa3b, v88
	v_exp_f32_e32 v94, v94
	s_nop 0
	v_add_f32_e32 v94, 1.0, v94
	v_rcp_f32_e32 v94, v94
	s_nop 0
	v_mul_f32_e32 v88, v88, v94
	v_mul_f32_e32 v84, v88, v84
	v_mul_f32_e32 v88, 0xbfb8aa3b, v89
	v_exp_f32_e32 v88, v88
	s_nop 0
	v_add_f32_e32 v88, 1.0, v88
	v_rcp_f32_e32 v88, v88
	s_nop 0
	v_mul_f32_e32 v88, v89, v88
	v_mul_f32_e32 v85, v88, v85
	v_cvt_pk_bf16_f32 v94, v84, v85
	v_mul_f32_e32 v84, 0xbfb8aa3b, v90
	v_exp_f32_e32 v84, v84
	v_mul_f32_e32 v85, 0xbfb8aa3b, v91
	v_exp_f32_e32 v85, v85
	v_add_f32_e32 v84, 1.0, v84
	v_rcp_f32_e32 v84, v84
	v_add_f32_e32 v85, 1.0, v85
	v_rcp_f32_e32 v85, v85
	v_mul_f32_e32 v84, v90, v84
	v_mul_f32_e32 v84, v84, v86
	v_mul_f32_e32 v86, 0xbfb8aa3b, v80
	v_exp_f32_e32 v86, v86
	v_mul_f32_e32 v85, v91, v85
	v_mul_f32_e32 v85, v85, v87
	v_cvt_pk_bf16_f32 v95, v84, v85
	v_add_f32_e32 v86, 1.0, v86
	v_rcp_f32_e32 v86, v86
	s_mov_b64 s[98:99], 0x42000
	v_mul_f32_e32 v80, v80, v86
	v_mul_f32_e32 v76, v80, v76
	v_mul_f32_e32 v80, 0xbfb8aa3b, v81
	v_exp_f32_e32 v80, v80
	v_lshl_add_u64 v[84:85], v[132:133], 0, s[98:99]
	global_store_dwordx4 v[100:101], v[92:95], off
	v_add_f32_e32 v80, 1.0, v80
	v_rcp_f32_e32 v80, v80
	s_nop 0
	v_mul_f32_e32 v80, v81, v80
	v_mul_f32_e32 v77, v80, v77
	v_cvt_pk_bf16_f32 v76, v76, v77
	v_mul_f32_e32 v77, 0xbfb8aa3b, v82
	v_exp_f32_e32 v77, v77
	s_nop 0
	v_add_f32_e32 v77, 1.0, v77
	v_rcp_f32_e32 v77, v77
	s_nop 0
	v_mul_f32_e32 v77, v82, v77
	v_mul_f32_e32 v77, v77, v78
	v_mul_f32_e32 v78, 0xbfb8aa3b, v83
	v_exp_f32_e32 v78, v78
	s_nop 0
	v_add_f32_e32 v78, 1.0, v78
	v_rcp_f32_e32 v78, v78
	s_nop 0
	v_mul_f32_e32 v78, v83, v78
	v_mul_f32_e32 v78, v78, v79
	v_cvt_pk_bf16_f32 v77, v77, v78
	v_mul_f32_e32 v78, 0xbfb8aa3b, v72
	v_exp_f32_e32 v78, v78
	s_nop 0
	v_add_f32_e32 v78, 1.0, v78
	v_rcp_f32_e32 v78, v78
	s_nop 0
	v_mul_f32_e32 v72, v72, v78
	v_mul_f32_e32 v68, v72, v68
	v_mul_f32_e32 v72, 0xbfb8aa3b, v73
	v_exp_f32_e32 v72, v72
	s_nop 0
	v_add_f32_e32 v72, 1.0, v72
	v_rcp_f32_e32 v72, v72
	s_nop 0
	v_mul_f32_e32 v72, v73, v72
	v_mul_f32_e32 v69, v72, v69
	v_cvt_pk_bf16_f32 v78, v68, v69
	v_mul_f32_e32 v68, 0xbfb8aa3b, v74
	v_exp_f32_e32 v68, v68
	v_mul_f32_e32 v69, 0xbfb8aa3b, v75
	v_exp_f32_e32 v69, v69
	v_add_f32_e32 v68, 1.0, v68
	v_rcp_f32_e32 v68, v68
	v_add_f32_e32 v69, 1.0, v69
	v_rcp_f32_e32 v69, v69
	v_mul_f32_e32 v68, v74, v68
	v_mul_f32_e32 v68, v68, v70
	v_mul_f32_e32 v70, 0xbfb8aa3b, v64
	v_exp_f32_e32 v70, v70
	v_mul_f32_e32 v69, v75, v69
	v_mul_f32_e32 v69, v69, v71
	v_cvt_pk_bf16_f32 v79, v68, v69
	v_add_f32_e32 v70, 1.0, v70
	v_rcp_f32_e32 v70, v70
	s_mov_b64 s[98:99], 0xb0000
	v_mul_f32_e32 v64, v64, v70
	v_mul_f32_e32 v60, v64, v60
; __device__ __forceinline__ unsigned pk2(float lo, float hi) { unsigned r; asm("v_cvt_pk_bf16_f32 %0, %1, %2" : "=v"(r) : "v"(lo), "v"(hi)); return r; }
; __device__ __forceinline__ float silu(float x) { return x * sigm(x); }
; #define PG8_WAIT_V(n) asm volatile("s_waitcnt vmcnt(" #n ")" ::: "memory")
; #define PG8_BAR __builtin_amdgcn_s_barrier()
;     __device__ __forceinline__ void operator()(const f32x4 (&acc)[2][2][4][2], const Unit& u, int wr, int wc, int fr, int fq) const {
;         const int row0 = u.pm * BM + wr * 64 + fr, col0 = u.pn * HALF + wc * 32 + 8 * fq;
; #pragma unroll
;         for (int ai = 0; ai < 2; ++ai)
; #pragma unroll
;             for (int m = 0; m < 4; ++m) { bf16_t* rowp = O + (size_t)(row0 + ai * HALF + m * 16) * ldc + col0;
;                 const f32x4 g0 = acc[ai][0][m][0], g1 = acc[ai][0][m][1], u0 = acc[ai][1][m][0], u1 = acc[ai][1][m][1];
;                 u32x4 w; w.x = pk2(silu(g0[0]) * u0[0], silu(g0[1]) * u0[1]); w.y = pk2(silu(g0[2]) * u0[2], silu(g0[3]) * u0[3]);
;                 w.z = pk2(silu(g1[0]) * u1[0], silu(g1[1]) * u1[1]); w.w = pk2(silu(g1[2]) * u1[2], silu(g1[3]) * u1[3]);
;                 *(u32x4*)rowp = w; }
; template <class Epi>
; __device__ __forceinline__ void gemm_phase(LAS unsigned char* lds, const Gemm g, const int G, const int cidx, const Epi& E) {
;     ...
;         if constexpr (!Epi::AFTER_DRAIN) E(acc, cur, wr, wc, fr, fq);
;         if (!has_next) break;
; #pragma unroll
;         for (int a = 0; a < 2; ++a)
; #pragma unroll
;             for (int b = 0; b < 2; ++b)
; #pragma unroll
;                 for (int m = 0; m < 4; ++m)
; #pragma unroll
;                     for (int n = 0; n < 2; ++n) acc[a][b][m][n] = ZERO4;
;         cur = nxt; cA = nA; cB = nB; ++ui;
;     }
;     PG8_WAIT_V(0);
;     if (wr == 0) PG8_BAR;
;     PG8_BAR;
	v_mul_f32_e32 v64, 0xbfb8aa3b, v65
	v_exp_f32_e32 v64, v64
	v_lshl_add_u64 v[68:69], v[132:133], 0, s[98:99]
	global_store_dwordx4 v[84:85], v[76:79], off
	v_add_f32_e32 v64, 1.0, v64
	v_rcp_f32_e32 v64, v64
	s_nop 0
	v_mul_f32_e32 v64, v65, v64
	v_mul_f32_e32 v61, v64, v61
	v_cvt_pk_bf16_f32 v60, v60, v61
	v_mul_f32_e32 v61, 0xbfb8aa3b, v66
	v_exp_f32_e32 v61, v61
	s_nop 0
	v_add_f32_e32 v61, 1.0, v61
	v_rcp_f32_e32 v61, v61
	s_nop 0
	v_mul_f32_e32 v61, v66, v61
	v_mul_f32_e32 v61, v61, v62
	v_mul_f32_e32 v62, 0xbfb8aa3b, v67
	v_exp_f32_e32 v62, v62
	s_nop 0
	v_add_f32_e32 v62, 1.0, v62
	v_rcp_f32_e32 v62, v62
	s_nop 0
	v_mul_f32_e32 v62, v67, v62
	v_mul_f32_e32 v62, v62, v63
	v_cvt_pk_bf16_f32 v61, v61, v62
	v_mul_f32_e32 v62, 0xbfb8aa3b, v56
	v_exp_f32_e32 v62, v62
	s_nop 0
	v_add_f32_e32 v62, 1.0, v62
	v_rcp_f32_e32 v62, v62
	s_nop 0
	v_mul_f32_e32 v56, v56, v62
	v_mul_f32_e32 v52, v56, v52
	v_mul_f32_e32 v56, 0xbfb8aa3b, v57
	v_exp_f32_e32 v56, v56
	s_nop 0
	v_add_f32_e32 v56, 1.0, v56
	v_rcp_f32_e32 v56, v56
	s_nop 0
	v_mul_f32_e32 v56, v57, v56
	v_mul_f32_e32 v53, v56, v53
	v_cvt_pk_bf16_f32 v62, v52, v53
	v_mul_f32_e32 v52, 0xbfb8aa3b, v58
	v_exp_f32_e32 v52, v52
	v_mul_f32_e32 v53, 0xbfb8aa3b, v59
	v_exp_f32_e32 v53, v53
	v_add_f32_e32 v52, 1.0, v52
	v_rcp_f32_e32 v52, v52
	v_add_f32_e32 v53, 1.0, v53
	v_rcp_f32_e32 v53, v53
	v_mul_f32_e32 v52, v58, v52
	v_mul_f32_e32 v52, v52, v54
	v_mul_f32_e32 v54, 0xbfb8aa3b, v48
	v_exp_f32_e32 v54, v54
	v_mul_f32_e32 v53, v59, v53
	v_mul_f32_e32 v53, v53, v55
	v_cvt_pk_bf16_f32 v63, v52, v53
	v_add_f32_e32 v54, 1.0, v54
	v_rcp_f32_e32 v54, v54
	s_mov_b64 s[98:99], 0xc6000
	v_mul_f32_e32 v48, v48, v54
	v_mul_f32_e32 v44, v48, v44
	v_mul_f32_e32 v48, 0xbfb8aa3b, v49
	v_exp_f32_e32 v48, v48
	v_lshl_add_u64 v[52:53], v[132:133], 0, s[98:99]
	global_store_dwordx4 v[68:69], v[60:63], off
	v_add_f32_e32 v48, 1.0, v48
	v_rcp_f32_e32 v48, v48
	s_nop 0
	v_mul_f32_e32 v48, v49, v48
	v_mul_f32_e32 v45, v48, v45
	v_cvt_pk_bf16_f32 v44, v44, v45
	v_mul_f32_e32 v45, 0xbfb8aa3b, v50
	v_exp_f32_e32 v45, v45
	s_nop 0
	v_add_f32_e32 v45, 1.0, v45
	v_rcp_f32_e32 v45, v45
	s_nop 0
	v_mul_f32_e32 v45, v50, v45
	v_mul_f32_e32 v45, v45, v46
	v_mul_f32_e32 v46, 0xbfb8aa3b, v51
	v_exp_f32_e32 v46, v46
	s_nop 0
	v_add_f32_e32 v46, 1.0, v46
	v_rcp_f32_e32 v46, v46
	s_nop 0
	v_mul_f32_e32 v46, v51, v46
	v_mul_f32_e32 v46, v46, v47
	v_cvt_pk_bf16_f32 v45, v45, v46
	v_mul_f32_e32 v46, 0xbfb8aa3b, v40
	v_exp_f32_e32 v46, v46
	s_nop 0
	v_add_f32_e32 v46, 1.0, v46
	v_rcp_f32_e32 v46, v46
	s_nop 0
	v_mul_f32_e32 v40, v40, v46
	v_mul_f32_e32 v36, v40, v36
	v_mul_f32_e32 v40, 0xbfb8aa3b, v41
	v_exp_f32_e32 v40, v40
	s_nop 0
	v_add_f32_e32 v40, 1.0, v40
	v_rcp_f32_e32 v40, v40
	s_nop 0
	v_mul_f32_e32 v40, v41, v40
	v_mul_f32_e32 v37, v40, v37
	v_cvt_pk_bf16_f32 v46, v36, v37
	v_mul_f32_e32 v36, 0xbfb8aa3b, v42
	v_exp_f32_e32 v36, v36
	v_mul_f32_e32 v37, 0xbfb8aa3b, v43
	v_exp_f32_e32 v37, v37
	v_add_f32_e32 v36, 1.0, v36
	v_rcp_f32_e32 v36, v36
	v_add_f32_e32 v37, 1.0, v37
	v_rcp_f32_e32 v37, v37
	v_mul_f32_e32 v36, v42, v36
	v_mul_f32_e32 v36, v36, v38
	v_mul_f32_e32 v38, 0xbfb8aa3b, v32
	v_exp_f32_e32 v38, v38
	v_mul_f32_e32 v37, v43, v37
	v_mul_f32_e32 v37, v37, v39
	v_cvt_pk_bf16_f32 v47, v36, v37
	v_add_f32_e32 v38, 1.0, v38
	v_rcp_f32_e32 v38, v38
	s_mov_b64 s[98:99], 0xdc000
	v_mul_f32_e32 v32, v32, v38
	v_mul_f32_e32 v28, v32, v28
	v_mul_f32_e32 v32, 0xbfb8aa3b, v33
	v_exp_f32_e32 v32, v32
	v_lshl_add_u64 v[36:37], v[132:133], 0, s[98:99]
	global_store_dwordx4 v[52:53], v[44:47], off
	v_add_f32_e32 v32, 1.0, v32
	v_rcp_f32_e32 v32, v32
	s_nop 0
	v_mul_f32_e32 v32, v33, v32
	v_mul_f32_e32 v29, v32, v29
	v_cvt_pk_bf16_f32 v28, v28, v29
	v_mul_f32_e32 v29, 0xbfb8aa3b, v34
	v_exp_f32_e32 v29, v29
	s_nop 0
	v_add_f32_e32 v29, 1.0, v29
	v_rcp_f32_e32 v29, v29
	s_nop 0
	v_mul_f32_e32 v29, v34, v29
	v_mul_f32_e32 v29, v29, v30
	v_mul_f32_e32 v30, 0xbfb8aa3b, v35
	v_exp_f32_e32 v30, v30
	s_nop 0
	v_add_f32_e32 v30, 1.0, v30
	v_rcp_f32_e32 v30, v30
	s_nop 0
	v_mul_f32_e32 v30, v35, v30
	v_mul_f32_e32 v30, v30, v31
	v_cvt_pk_bf16_f32 v29, v29, v30
	v_mul_f32_e32 v30, 0xbfb8aa3b, v24
	v_exp_f32_e32 v30, v30
	s_nop 0
	v_add_f32_e32 v30, 1.0, v30
	v_rcp_f32_e32 v30, v30
	s_nop 0
	v_mul_f32_e32 v24, v24, v30
	v_mul_f32_e32 v20, v24, v20
	v_mul_f32_e32 v24, 0xbfb8aa3b, v25
	v_exp_f32_e32 v24, v24
	s_nop 0
	v_add_f32_e32 v24, 1.0, v24
	v_rcp_f32_e32 v24, v24
	s_nop 0
	v_mul_f32_e32 v24, v25, v24
	v_mul_f32_e32 v21, v24, v21
	v_cvt_pk_bf16_f32 v30, v20, v21
	v_mul_f32_e32 v20, 0xbfb8aa3b, v26
	v_exp_f32_e32 v20, v20
	v_mul_f32_e32 v21, 0xbfb8aa3b, v27
	v_exp_f32_e32 v21, v21
	v_add_f32_e32 v20, 1.0, v20
	v_rcp_f32_e32 v20, v20
	v_add_f32_e32 v21, 1.0, v21
	v_rcp_f32_e32 v21, v21
	v_mul_f32_e32 v20, v26, v20
	v_mul_f32_e32 v20, v20, v22
	v_mul_f32_e32 v22, 0xbfb8aa3b, v16
	v_exp_f32_e32 v22, v22
	v_mul_f32_e32 v21, v27, v21
	v_mul_f32_e32 v21, v21, v23
	v_cvt_pk_bf16_f32 v31, v20, v21
	v_add_f32_e32 v22, 1.0, v22
	v_rcp_f32_e32 v22, v22
	s_mov_b64 s[98:99], 0xf2000
	v_mul_f32_e32 v16, v16, v22
	v_mul_f32_e32 v12, v16, v12
	v_mul_f32_e32 v16, 0xbfb8aa3b, v17
	v_exp_f32_e32 v16, v16
	v_lshl_add_u64 v[20:21], v[132:133], 0, s[98:99]
	s_mov_b32 s16, s8
	global_store_dwordx4 v[36:37], v[28:31], off
	v_add_f32_e32 v16, 1.0, v16
	v_rcp_f32_e32 v16, v16
	s_nop 0
	v_mul_f32_e32 v16, v17, v16
	v_mul_f32_e32 v13, v16, v13
	v_cvt_pk_bf16_f32 v12, v12, v13
	v_mul_f32_e32 v13, 0xbfb8aa3b, v18
	v_exp_f32_e32 v13, v13
	s_nop 0
	v_add_f32_e32 v13, 1.0, v13
	v_rcp_f32_e32 v13, v13
	s_nop 0
	v_mul_f32_e32 v13, v18, v13
	v_mul_f32_e32 v13, v13, v14
	v_mul_f32_e32 v14, 0xbfb8aa3b, v19
	v_exp_f32_e32 v14, v14
	s_nop 0
	v_add_f32_e32 v14, 1.0, v14
	v_rcp_f32_e32 v14, v14
	s_nop 0
	v_mul_f32_e32 v14, v19, v14
	v_mul_f32_e32 v14, v14, v15
	v_cvt_pk_bf16_f32 v13, v13, v14
	v_mul_f32_e32 v14, 0xbfb8aa3b, v8
	v_exp_f32_e32 v14, v14
	s_nop 0
	v_add_f32_e32 v14, 1.0, v14
	v_rcp_f32_e32 v14, v14
	s_nop 0
	v_mul_f32_e32 v8, v8, v14
	v_mul_f32_e32 v4, v8, v4
	v_mul_f32_e32 v8, 0xbfb8aa3b, v9
	v_exp_f32_e32 v8, v8
	s_nop 0
	v_add_f32_e32 v8, 1.0, v8
	v_rcp_f32_e32 v8, v8
	s_nop 0
	v_mul_f32_e32 v8, v9, v8
	v_mul_f32_e32 v5, v8, v5
	v_cvt_pk_bf16_f32 v14, v4, v5
	v_mul_f32_e32 v4, 0xbfb8aa3b, v10
	v_mul_f32_e32 v5, 0xbfb8aa3b, v11
	v_exp_f32_e32 v4, v4
	v_exp_f32_e32 v5, v5
	v_add_f32_e32 v4, 1.0, v4
	v_add_f32_e32 v5, 1.0, v5
	v_rcp_f32_e32 v4, v4
	v_rcp_f32_e32 v5, v5
	v_mul_f32_e32 v4, v10, v4
	v_mul_f32_e32 v5, v11, v5
	v_mul_f32_e32 v4, v4, v6
	v_mul_f32_e32 v5, v5, v7
	v_cvt_pk_bf16_f32 v15, v4, v5
	global_store_dwordx4 v[20:21], v[12:15], off
	s_cbranch_vccz .LBB0_79
	s_waitcnt vmcnt(0)
	s_cmpk_gt_u32 s95, 0xff
	s_mov_b32 s73, s83
	v_readlane_b32 s79, v255, 21
	s_cbranch_scc1 .LBB0_86
	s_barrier

; #define PG8_STAGE(bufoff, gbase, voff) do { _Pragma("unroll") for (int _i = 0; _i < 2; ++_i) \
;         __builtin_amdgcn_global_load_lds((const unsigned*)((const char*)(gbase) + (voff)[_i]), (LAS unsigned*)(lds + (bufoff) + ldsw + _i * 8192), 16, 0, 0); } while (0)
; #define PG8_LDA(dst, b, h) do { _Pragma("unroll") for (int m = 0; m < 4; ++m) _Pragma("unroll") for (int k = 0; k < 2; ++k) dst[m][k] = *(const LAS bf16x8*)(lds + PG8_SA(b, h) + aoff + m * 2048 + k * 1024); } while (0)
; #define PG8_LDB(dst, b, h) do { _Pragma("unroll") for (int n = 0; n < 2; ++n) _Pragma("unroll") for (int k = 0; k < 2; ++k) dst[n][k] = *(const LAS bf16x8*)(lds + PG8_SB(b, h) + boff + n * 2048 + k * 1024); } while (0)
; #define PG8_MMA(ai, bj, At, Bt) do { __builtin_amdgcn_s_setprio(1); _Pragma("unroll") for (int m = 0; m < 4; ++m) _Pragma("unroll") for (int n = 0; n < 2; ++n) _Pragma("unroll") for (int k = 0; k < 2; ++k) \
;         acc[ai][bj][m][n] = __builtin_amdgcn_mfma_f32_16x16x32_bf16(Bt[n][k], At[m][k], acc[ai][bj][m][n], 0, 0, 0); __builtin_amdgcn_s_setprio(0); } while (0)
; #define PG8_WAIT_V(n) asm volatile("s_waitcnt vmcnt(" #n ")" ::: "memory")
; #define PG8_WAIT_L(n) asm volatile("s_waitcnt lgkmcnt(" #n ")" ::: "memory")
; #define PG8_BAR __builtin_amdgcn_s_barrier()
; #define PG8_SCHED __builtin_amdgcn_sched_barrier(0)
; template <class Epi>
; __device__ __forceinline__ void gemm_phase(LAS unsigned char* lds, const Gemm g, const int G, const int cidx, const Epi& E) {
;     ...
;             const char* a1 = cA + (size_t)(t + 1) * kstep;
;             const char* a2 = last ? nA : cA + (size_t)(t + 2) * kstep; const char* b2 = last ? nB : cB + (size_t)(t + 2) * kstep;
;             const char* a3 = a2 + kstep; const char* b3 = b2 + kstep;
;             PG8_LDB(B0, 0, 0); PG8_LDB(B1, 0, 1); PG8_SCHED; PG8_LDA(At, 0, 0); PG8_STAGE(PG8_SA(1, 1), a1 + hstep, voffA);
;             PG8_WAIT_V(8); PG8_WAIT_L(0); PG8_BAR; PG8_MMA(0, 0, At, B0); PG8_MMA(0, 1, At, B1); PG8_BAR; PG8_SCHED;
;             PG8_LDA(At, 0, 1); PG8_STAGE(PG8_SB(0, 0), b2, voffB); PG8_STAGE(PG8_SB(0, 1), b2 + hstep, voffB); PG8_STAGE(PG8_SA(0, 0), a2, voffA);
.LBB0_216:
	s_add_i32 s87, 0, 0x10000
	v_add_u32_e32 v3, s87, v158
	ds_read_b128 v[132:135], v3
	ds_read_b128 v[140:143], v3 offset:1024
	ds_read_b128 v[160:163], v3 offset:2048
	ds_read_b128 v[164:167], v3 offset:3072
	s_add_i32 s83, 0, 0x14000
	v_add_u32_e32 v3, s83, v158
	ds_read_b128 v[168:171], v3
	ds_read_b128 v[172:175], v3 offset:1024
	ds_read_b128 v[176:179], v3 offset:2048
	ds_read_b128 v[180:183], v3 offset:3072
	v_lshl_add_u64 v[200:201], v[154:155], 0, s[70:71]
	s_add_i32 m0, s19, 0xc000
	ds_read_b128 v[184:187], v159
	ds_read_b128 v[188:191], v159 offset:1024
	ds_read_b128 v[192:195], v159 offset:2048
	ds_read_b128 v[196:199], v159 offset:3072
	ds_read_b128 v[214:217], v159 offset:4096
	ds_read_b128 v[218:221], v159 offset:5120
	ds_read_b128 v[222:225], v159 offset:6144
	ds_read_b128 v[226:229], v159 offset:7168
	s_add_u32 s72, s8, s70
	s_addc_u32 s73, s9, s71
	s_add_u32 s72, s72, 0x100
	s_addc_u32 s73, s73, 0
	s_add_u32 s83, s43, s70
	s_addc_u32 s86, s44, s71
	s_cmpk_eq_i32 s70, 0x700
	s_cselect_b32 s75, s31, s73
	s_cselect_b32 s74, s45, s72
	s_cselect_b32 s73, s29, s86
	s_cselect_b32 s72, s68, s83
	s_add_i32 s83, 0, 0x14000
	global_load_lds_dwordx4 v[200:201], off
	v_lshl_add_u64 v[200:201], v[0:1], 0, s[70:71]
	s_add_i32 m0, s19, 0xe000
	s_nop 0
	global_load_lds_dwordx4 v[200:201], off
	s_waitcnt vmcnt(8)
	s_waitcnt lgkmcnt(0)
	s_barrier
	s_setprio 1
	s_waitcnt lgkmcnt(0)
	v_mfma_f32_16x16x32_bf16 v[64:67], v[132:135], v[184:187], v[64:67]
	v_mfma_f32_16x16x32_bf16 v[72:75], v[160:163], v[184:187], v[72:75]
	v_mfma_f32_16x16x32_bf16 v[92:95], v[132:135], v[192:195], v[92:95]
	v_mfma_f32_16x16x32_bf16 v[96:99], v[160:163], v[192:195], v[96:99]
	v_mfma_f32_16x16x32_bf16 v[116:119], v[132:135], v[214:217], v[116:119]
	v_mfma_f32_16x16x32_bf16 v[124:127], v[160:163], v[214:217], v[124:127]
	v_mfma_f32_16x16x32_bf16 v[112:115], v[132:135], v[222:225], v[112:115]
	v_mfma_f32_16x16x32_bf16 v[100:103], v[160:163], v[222:225], v[100:103]
	v_mfma_f32_16x16x32_bf16 v[64:67], v[140:143], v[188:191], v[64:67]
	v_mfma_f32_16x16x32_bf16 v[72:75], v[164:167], v[188:191], v[72:75]
	v_mfma_f32_16x16x32_bf16 v[92:95], v[140:143], v[196:199], v[92:95]
	v_mfma_f32_16x16x32_bf16 v[96:99], v[164:167], v[196:199], v[96:99]
	v_mfma_f32_16x16x32_bf16 v[116:119], v[140:143], v[218:221], v[116:119]
	v_mfma_f32_16x16x32_bf16 v[124:127], v[164:167], v[218:221], v[124:127]
	v_mfma_f32_16x16x32_bf16 v[112:115], v[140:143], v[226:229], v[112:115]
	v_mfma_f32_16x16x32_bf16 v[100:103], v[164:167], v[226:229], v[100:103]
	s_setprio 0
	s_setprio 1
	v_mfma_f32_16x16x32_bf16 v[76:79], v[168:171], v[184:187], v[76:79]
	v_mfma_f32_16x16x32_bf16 v[84:87], v[176:179], v[184:187], v[84:87]
	v_mfma_f32_16x16x32_bf16 v[104:107], v[168:171], v[192:195], v[104:107]
	v_mfma_f32_16x16x32_bf16 v[108:111], v[176:179], v[192:195], v[108:111]
	v_mfma_f32_16x16x32_bf16 v[128:131], v[168:171], v[214:217], v[128:131]
	v_mfma_f32_16x16x32_bf16 v[120:123], v[176:179], v[214:217], v[120:123]
	v_mfma_f32_16x16x32_bf16 v[88:91], v[168:171], v[222:225], v[88:91]
	v_mfma_f32_16x16x32_bf16 v[80:83], v[176:179], v[222:225], v[80:83]
	v_mfma_f32_16x16x32_bf16 v[76:79], v[172:175], v[188:191], v[76:79]
	v_mfma_f32_16x16x32_bf16 v[84:87], v[180:183], v[188:191], v[84:87]
	v_mfma_f32_16x16x32_bf16 v[104:107], v[172:175], v[196:199], v[104:107]
	v_mfma_f32_16x16x32_bf16 v[108:111], v[180:183], v[196:199], v[108:111]
	v_mfma_f32_16x16x32_bf16 v[128:131], v[172:175], v[218:221], v[128:131]
	v_mfma_f32_16x16x32_bf16 v[120:123], v[180:183], v[218:221], v[120:123]
	v_mfma_f32_16x16x32_bf16 v[88:91], v[172:175], v[226:229], v[88:91]
	v_mfma_f32_16x16x32_bf16 v[80:83], v[180:183], v[226:229], v[80:83]
	s_setprio 0
	s_barrier
	s_add_i32 s86, s87, s40
	v_lshl_add_u64 v[200:201], s[72:73], 0, v[146:147]
	s_mov_b32 m0, s86
	ds_read_b128 v[184:187], v159 offset:16384
	ds_read_b128 v[188:191], v159 offset:17408
	ds_read_b128 v[192:195], v159 offset:18432
	ds_read_b128 v[196:199], v159 offset:19456
	ds_read_b128 v[214:217], v159 offset:20480
	ds_read_b128 v[218:221], v159 offset:21504
	ds_read_b128 v[222:225], v159 offset:22528
	ds_read_b128 v[226:229], v159 offset:23552
	global_load_lds_dwordx4 v[200:201], off
	s_add_i32 m0, s86, 0x2000
	s_add_u32 s86, s72, 0x40000
	v_lshl_add_u64 v[230:231], s[72:73], 0, v[148:149]
	s_addc_u32 s87, s73, 0
	s_add_i32 s83, s83, s40
	global_load_lds_dwordx4 v[230:231], off
	v_lshl_add_u64 v[232:233], s[86:87], 0, v[146:147]
	s_mov_b32 m0, s83
	v_lshl_add_u64 v[234:235], s[74:75], 0, v[148:149]
	global_load_lds_dwordx4 v[232:233], off
	v_lshl_add_u64 v[232:233], s[86:87], 0, v[148:149]
	s_add_i32 m0, s83, 0x2000
	s_nop 0
	global_load_lds_dwordx4 v[232:233], off
	v_lshl_add_u64 v[232:233], s[74:75], 0, v[146:147]
	s_mov_b32 m0, s19
	s_nop 0
	global_load_lds_dwordx4 v[232:233], off
	s_mov_b32 m0, s76
	s_nop 0
	global_load_lds_dwordx4 v[234:235], off
	s_waitcnt vmcnt(8)
	s_waitcnt lgkmcnt(0)
	s_barrier
; #define PG8_STAGE(bufoff, gbase, voff) do { _Pragma("unroll") for (int _i = 0; _i < 2; ++_i) \
;         __builtin_amdgcn_global_load_lds((const unsigned*)((const char*)(gbase) + (voff)[_i]), (LAS unsigned*)(lds + (bufoff) + ldsw + _i * 8192), 16, 0, 0); } while (0)
; #define PG8_LDA(dst, b, h) do { _Pragma("unroll") for (int m = 0; m < 4; ++m) _Pragma("unroll") for (int k = 0; k < 2; ++k) dst[m][k] = *(const LAS bf16x8*)(lds + PG8_SA(b, h) + aoff + m * 2048 + k * 1024); } while (0)
; #define PG8_LDB(dst, b, h) do { _Pragma("unroll") for (int n = 0; n < 2; ++n) _Pragma("unroll") for (int k = 0; k < 2; ++k) dst[n][k] = *(const LAS bf16x8*)(lds + PG8_SB(b, h) + boff + n * 2048 + k * 1024); } while (0)
; #define PG8_MMA(ai, bj, At, Bt) do { __builtin_amdgcn_s_setprio(1); _Pragma("unroll") for (int m = 0; m < 4; ++m) _Pragma("unroll") for (int n = 0; n < 2; ++n) _Pragma("unroll") for (int k = 0; k < 2; ++k) \
;         acc[ai][bj][m][n] = __builtin_amdgcn_mfma_f32_16x16x32_bf16(Bt[n][k], At[m][k], acc[ai][bj][m][n], 0, 0, 0); __builtin_amdgcn_s_setprio(0); } while (0)
; #define PG8_WAIT_V(n) asm volatile("s_waitcnt vmcnt(" #n ")" ::: "memory")
; #define PG8_WAIT_L(n) asm volatile("s_waitcnt lgkmcnt(" #n ")" ::: "memory")
; #define PG8_BAR __builtin_amdgcn_s_barrier()
; #define PG8_SCHED __builtin_amdgcn_sched_barrier(0)
; template <class Epi>
; __device__ __forceinline__ void gemm_phase(LAS unsigned char* lds, const Gemm g, const int G, const int cidx, const Epi& E) {
;     ...
;             PG8_WAIT_V(8); PG8_WAIT_L(0); PG8_BAR; PG8_MMA(0, 0, At, B0); PG8_MMA(0, 1, At, B1); PG8_BAR; PG8_SCHED;
;             PG8_LDA(At, 0, 1); PG8_STAGE(PG8_SB(0, 0), b2, voffB); PG8_STAGE(PG8_SB(0, 1), b2 + hstep, voffB); PG8_STAGE(PG8_SA(0, 0), a2, voffA);
;             PG8_WAIT_V(8); PG8_WAIT_L(0); PG8_BAR; PG8_MMA(1, 0, At, B0); PG8_MMA(1, 1, At, B1); PG8_BAR; PG8_SCHED;
;             PG8_LDB(B0, 1, 0); PG8_LDB(B1, 1, 1); PG8_SCHED; PG8_LDA(At, 1, 0); PG8_STAGE(PG8_SA(0, 1), a2 + hstep, voffA);
;             PG8_WAIT_V(8); PG8_WAIT_L(0); PG8_BAR; PG8_MMA(0, 0, At, B0); PG8_MMA(0, 1, At, B1); PG8_BAR; PG8_SCHED;
;             PG8_LDA(At, 1, 1); PG8_STAGE(PG8_SB(1, 0), b3, voffB); PG8_STAGE(PG8_SB(1, 1), b3 + hstep, voffB); PG8_STAGE(PG8_SA(1, 0), a3, voffA);
;             PG8_WAIT_V(8); PG8_WAIT_L(0); PG8_BAR; PG8_MMA(1, 0, At, B0); PG8_MMA(1, 1, At, B1); PG8_BAR; PG8_SCHED;
	s_setprio 1
	s_waitcnt lgkmcnt(0)
	v_mfma_f32_16x16x32_bf16 v[68:71], v[132:135], v[184:187], v[68:71]
	v_mfma_f32_16x16x32_bf16 v[60:63], v[160:163], v[184:187], v[60:63]
	v_mfma_f32_16x16x32_bf16 v[48:51], v[132:135], v[192:195], v[48:51]
	v_mfma_f32_16x16x32_bf16 v[44:47], v[160:163], v[192:195], v[44:47]
	v_mfma_f32_16x16x32_bf16 v[32:35], v[132:135], v[214:217], v[32:35]
	v_mfma_f32_16x16x32_bf16 v[28:31], v[160:163], v[214:217], v[28:31]
	v_mfma_f32_16x16x32_bf16 v[16:19], v[132:135], v[222:225], v[16:19]
	v_mfma_f32_16x16x32_bf16 v[12:15], v[160:163], v[222:225], v[12:15]
	v_mfma_f32_16x16x32_bf16 v[68:71], v[140:143], v[188:191], v[68:71]
	v_mfma_f32_16x16x32_bf16 v[60:63], v[164:167], v[188:191], v[60:63]
	v_mfma_f32_16x16x32_bf16 v[48:51], v[140:143], v[196:199], v[48:51]
	v_mfma_f32_16x16x32_bf16 v[44:47], v[164:167], v[196:199], v[44:47]
	v_mfma_f32_16x16x32_bf16 v[32:35], v[140:143], v[218:221], v[32:35]
	v_mfma_f32_16x16x32_bf16 v[28:31], v[164:167], v[218:221], v[28:31]
	v_mfma_f32_16x16x32_bf16 v[16:19], v[140:143], v[226:229], v[16:19]
	v_mfma_f32_16x16x32_bf16 v[12:15], v[164:167], v[226:229], v[12:15]
	s_setprio 0
	s_setprio 1
	v_mfma_f32_16x16x32_bf16 v[56:59], v[168:171], v[184:187], v[56:59]
	v_mfma_f32_16x16x32_bf16 v[52:55], v[176:179], v[184:187], v[52:55]
	v_mfma_f32_16x16x32_bf16 v[40:43], v[168:171], v[192:195], v[40:43]
	v_mfma_f32_16x16x32_bf16 v[36:39], v[176:179], v[192:195], v[36:39]
	v_mfma_f32_16x16x32_bf16 v[24:27], v[168:171], v[214:217], v[24:27]
	v_mfma_f32_16x16x32_bf16 v[20:23], v[176:179], v[214:217], v[20:23]
	v_mfma_f32_16x16x32_bf16 v[8:11], v[168:171], v[222:225], v[8:11]
	v_mfma_f32_16x16x32_bf16 v[4:7], v[176:179], v[222:225], v[4:7]
	v_mfma_f32_16x16x32_bf16 v[56:59], v[172:175], v[188:191], v[56:59]
	v_mfma_f32_16x16x32_bf16 v[52:55], v[180:183], v[188:191], v[52:55]
	v_mfma_f32_16x16x32_bf16 v[40:43], v[172:175], v[196:199], v[40:43]
	v_mfma_f32_16x16x32_bf16 v[36:39], v[180:183], v[196:199], v[36:39]
	v_mfma_f32_16x16x32_bf16 v[24:27], v[172:175], v[218:221], v[24:27]
	v_mfma_f32_16x16x32_bf16 v[20:23], v[180:183], v[218:221], v[20:23]
	v_mfma_f32_16x16x32_bf16 v[8:11], v[172:175], v[226:229], v[8:11]
	v_mfma_f32_16x16x32_bf16 v[4:7], v[180:183], v[226:229], v[4:7]
	s_setprio 0
	s_barrier
	s_add_i32 s83, 0, 0x18000
	v_add_u32_e32 v3, s83, v158
	s_add_i32 s86, 0, 0x1c000
	ds_read_b128 v[132:135], v3
	ds_read_b128 v[140:143], v3 offset:1024
	ds_read_b128 v[160:163], v3 offset:2048
	ds_read_b128 v[164:167], v3 offset:3072
	v_add_u32_e32 v3, s86, v158
	ds_read_b128 v[168:171], v3
	ds_read_b128 v[172:175], v3 offset:1024
	ds_read_b128 v[176:179], v3 offset:2048
	ds_read_b128 v[180:183], v3 offset:3072
	s_add_u32 s74, s74, 0x40000
	s_addc_u32 s75, s75, 0
	s_mov_b32 m0, s84
	v_lshl_add_u64 v[236:237], s[74:75], 0, v[146:147]
	ds_read_b128 v[184:187], v159 offset:32768
	ds_read_b128 v[188:191], v159 offset:33792
	ds_read_b128 v[192:195], v159 offset:34816
	ds_read_b128 v[196:199], v159 offset:35840
	ds_read_b128 v[214:217], v159 offset:36864
	ds_read_b128 v[218:221], v159 offset:37888
	ds_read_b128 v[222:225], v159 offset:38912
	ds_read_b128 v[226:229], v159 offset:39936
	global_load_lds_dwordx4 v[236:237], off
	v_lshl_add_u64 v[236:237], s[74:75], 0, v[148:149]
	s_mov_b32 m0, s97
	s_nop 0
	global_load_lds_dwordx4 v[236:237], off
	s_waitcnt vmcnt(8)
	s_waitcnt lgkmcnt(0)
	s_barrier
	s_setprio 1
	s_waitcnt lgkmcnt(0)
	v_mfma_f32_16x16x32_bf16 v[64:67], v[132:135], v[184:187], v[64:67]
	v_mfma_f32_16x16x32_bf16 v[72:75], v[160:163], v[184:187], v[72:75]
	v_mfma_f32_16x16x32_bf16 v[92:95], v[132:135], v[192:195], v[92:95]
	v_mfma_f32_16x16x32_bf16 v[96:99], v[160:163], v[192:195], v[96:99]
	v_mfma_f32_16x16x32_bf16 v[116:119], v[132:135], v[214:217], v[116:119]
	v_mfma_f32_16x16x32_bf16 v[124:127], v[160:163], v[214:217], v[124:127]
	v_mfma_f32_16x16x32_bf16 v[112:115], v[132:135], v[222:225], v[112:115]
	v_mfma_f32_16x16x32_bf16 v[100:103], v[160:163], v[222:225], v[100:103]
	v_mfma_f32_16x16x32_bf16 v[64:67], v[140:143], v[188:191], v[64:67]
	v_mfma_f32_16x16x32_bf16 v[72:75], v[164:167], v[188:191], v[72:75]
	v_mfma_f32_16x16x32_bf16 v[92:95], v[140:143], v[196:199], v[92:95]
	v_mfma_f32_16x16x32_bf16 v[96:99], v[164:167], v[196:199], v[96:99]
	v_mfma_f32_16x16x32_bf16 v[116:119], v[140:143], v[218:221], v[116:119]
	v_mfma_f32_16x16x32_bf16 v[124:127], v[164:167], v[218:221], v[124:127]
	v_mfma_f32_16x16x32_bf16 v[112:115], v[140:143], v[226:229], v[112:115]
	v_mfma_f32_16x16x32_bf16 v[100:103], v[164:167], v[226:229], v[100:103]
	s_setprio 0
	s_setprio 1
	v_mfma_f32_16x16x32_bf16 v[76:79], v[168:171], v[184:187], v[76:79]
	v_mfma_f32_16x16x32_bf16 v[84:87], v[176:179], v[184:187], v[84:87]
	v_mfma_f32_16x16x32_bf16 v[104:107], v[168:171], v[192:195], v[104:107]
	v_mfma_f32_16x16x32_bf16 v[108:111], v[176:179], v[192:195], v[108:111]
	v_mfma_f32_16x16x32_bf16 v[128:131], v[168:171], v[214:217], v[128:131]
	v_mfma_f32_16x16x32_bf16 v[120:123], v[176:179], v[214:217], v[120:123]
	v_mfma_f32_16x16x32_bf16 v[88:91], v[168:171], v[222:225], v[88:91]
	v_mfma_f32_16x16x32_bf16 v[80:83], v[176:179], v[222:225], v[80:83]
	v_mfma_f32_16x16x32_bf16 v[76:79], v[172:175], v[188:191], v[76:79]
	v_mfma_f32_16x16x32_bf16 v[84:87], v[180:183], v[188:191], v[84:87]
	v_mfma_f32_16x16x32_bf16 v[104:107], v[172:175], v[196:199], v[104:107]
	v_mfma_f32_16x16x32_bf16 v[108:111], v[180:183], v[196:199], v[108:111]
	v_mfma_f32_16x16x32_bf16 v[128:131], v[172:175], v[218:221], v[128:131]
	v_mfma_f32_16x16x32_bf16 v[120:123], v[180:183], v[218:221], v[120:123]
	v_mfma_f32_16x16x32_bf16 v[88:91], v[172:175], v[226:229], v[88:91]
	v_mfma_f32_16x16x32_bf16 v[80:83], v[180:183], v[226:229], v[80:83]
	s_setprio 0
	s_barrier
; #define PG8_STAGE(bufoff, gbase, voff) do { _Pragma("unroll") for (int _i = 0; _i < 2; ++_i) \
;         __builtin_amdgcn_global_load_lds((const unsigned*)((const char*)(gbase) + (voff)[_i]), (LAS unsigned*)(lds + (bufoff) + ldsw + _i * 8192), 16, 0, 0); } while (0)
; #define PG8_LDA(dst, b, h) do { _Pragma("unroll") for (int m = 0; m < 4; ++m) _Pragma("unroll") for (int k = 0; k < 2; ++k) dst[m][k] = *(const LAS bf16x8*)(lds + PG8_SA(b, h) + aoff + m * 2048 + k * 1024); } while (0)
; #define PG8_LDB(dst, b, h) do { _Pragma("unroll") for (int n = 0; n < 2; ++n) _Pragma("unroll") for (int k = 0; k < 2; ++k) dst[n][k] = *(const LAS bf16x8*)(lds + PG8_SB(b, h) + boff + n * 2048 + k * 1024); } while (0)
; #define PG8_MMA(ai, bj, At, Bt) do { __builtin_amdgcn_s_setprio(1); _Pragma("unroll") for (int m = 0; m < 4; ++m) _Pragma("unroll") for (int n = 0; n < 2; ++n) _Pragma("unroll") for (int k = 0; k < 2; ++k) \
;         acc[ai][bj][m][n] = __builtin_amdgcn_mfma_f32_16x16x32_bf16(Bt[n][k], At[m][k], acc[ai][bj][m][n], 0, 0, 0); __builtin_amdgcn_s_setprio(0); } while (0)
; #define PG8_WAIT_V(n) asm volatile("s_waitcnt vmcnt(" #n ")" ::: "memory")
; template <class Epi>
; __device__ __forceinline__ void gemm_phase(LAS unsigned char* lds, const Gemm g, const int G, const int cidx, const Epi& E) {
;     ...
;             PG8_WAIT_V(8); PG8_WAIT_L(0); PG8_BAR; PG8_MMA(1, 0, At, B0); PG8_MMA(1, 1, At, B1); PG8_BAR; PG8_SCHED;
;             PG8_LDB(B0, 1, 0); PG8_LDB(B1, 1, 1); PG8_SCHED; PG8_LDA(At, 1, 0); PG8_STAGE(PG8_SA(0, 1), a2 + hstep, voffA);
;             PG8_WAIT_V(8); PG8_WAIT_L(0); PG8_BAR; PG8_MMA(0, 0, At, B0); PG8_MMA(0, 1, At, B1); PG8_BAR; PG8_SCHED;
;             PG8_LDA(At, 1, 1); PG8_STAGE(PG8_SB(1, 0), b3, voffB); PG8_STAGE(PG8_SB(1, 1), b3 + hstep, voffB); PG8_STAGE(PG8_SA(1, 0), a3, voffA);
;             PG8_WAIT_V(8); PG8_WAIT_L(0); PG8_BAR; PG8_MMA(1, 0, At, B0); PG8_MMA(1, 1, At, B1); PG8_BAR; PG8_SCHED;
;         }
;         if constexpr (!Epi::AFTER_DRAIN) E(acc, cur, wr, wc, fr, fq);
;         if (!has_next) break;
; #pragma unroll
;         for (int a = 0; a < 2; ++a)
; #pragma unroll
;             for (int b = 0; b < 2; ++b)
; #pragma unroll
;                 for (int m = 0; m < 4; ++m)
; #pragma unroll
;                     for (int n = 0; n < 2; ++n) acc[a][b][m][n] = ZERO4;
;         cur = nxt; cA = nA; cB = nB; ++ui;
	s_add_i32 s74, s83, s40
	v_lshl_add_u64 v[200:201], v[200:201], 0, s[46:47]
	s_mov_b32 m0, s74
	ds_read_b128 v[184:187], v159 offset:49152
	ds_read_b128 v[188:191], v159 offset:50176
	ds_read_b128 v[192:195], v159 offset:51200
	ds_read_b128 v[196:199], v159 offset:52224
	ds_read_b128 v[214:217], v159 offset:53248
	ds_read_b128 v[218:221], v159 offset:54272
	ds_read_b128 v[222:225], v159 offset:55296
	ds_read_b128 v[226:229], v159 offset:56320
	global_load_lds_dwordx4 v[200:201], off
	s_add_i32 m0, s74, 0x2000
	s_add_u32 s72, s72, 0x40080
	v_lshl_add_u64 v[200:201], v[230:231], 0, s[46:47]
	s_addc_u32 s73, s73, 0
	s_add_i32 s74, s86, s40
	global_load_lds_dwordx4 v[200:201], off
	v_lshl_add_u64 v[200:201], s[72:73], 0, v[146:147]
	s_mov_b32 m0, s74
	s_nop 0
	global_load_lds_dwordx4 v[200:201], off
	v_lshl_add_u64 v[200:201], s[72:73], 0, v[148:149]
	s_add_i32 m0, s74, 0x2000
	s_nop 0
	global_load_lds_dwordx4 v[200:201], off
	v_lshl_add_u64 v[200:201], v[232:233], 0, s[46:47]
	s_mov_b32 m0, s0
	s_nop 0
	global_load_lds_dwordx4 v[200:201], off
	v_lshl_add_u64 v[200:201], v[234:235], 0, s[46:47]
	s_mov_b32 m0, s2
	s_nop 0
	global_load_lds_dwordx4 v[200:201], off
	s_waitcnt vmcnt(8)
	s_waitcnt lgkmcnt(0)
	s_barrier
	s_setprio 1
	s_waitcnt lgkmcnt(0)
	v_mfma_f32_16x16x32_bf16 v[68:71], v[132:135], v[184:187], v[68:71]
	v_mfma_f32_16x16x32_bf16 v[60:63], v[160:163], v[184:187], v[60:63]
	v_mfma_f32_16x16x32_bf16 v[48:51], v[132:135], v[192:195], v[48:51]
	v_mfma_f32_16x16x32_bf16 v[44:47], v[160:163], v[192:195], v[44:47]
	v_mfma_f32_16x16x32_bf16 v[32:35], v[132:135], v[214:217], v[32:35]
	v_mfma_f32_16x16x32_bf16 v[28:31], v[160:163], v[214:217], v[28:31]
	v_mfma_f32_16x16x32_bf16 v[16:19], v[132:135], v[222:225], v[16:19]
	v_mfma_f32_16x16x32_bf16 v[12:15], v[160:163], v[222:225], v[12:15]
	v_mfma_f32_16x16x32_bf16 v[68:71], v[140:143], v[188:191], v[68:71]
	v_mfma_f32_16x16x32_bf16 v[60:63], v[164:167], v[188:191], v[60:63]
	v_mfma_f32_16x16x32_bf16 v[48:51], v[140:143], v[196:199], v[48:51]
	v_mfma_f32_16x16x32_bf16 v[44:47], v[164:167], v[196:199], v[44:47]
	v_mfma_f32_16x16x32_bf16 v[32:35], v[140:143], v[218:221], v[32:35]
	v_mfma_f32_16x16x32_bf16 v[28:31], v[164:167], v[218:221], v[28:31]
	v_mfma_f32_16x16x32_bf16 v[16:19], v[140:143], v[226:229], v[16:19]
	v_mfma_f32_16x16x32_bf16 v[12:15], v[164:167], v[226:229], v[12:15]
	s_setprio 0
	s_setprio 1
	v_mfma_f32_16x16x32_bf16 v[56:59], v[168:171], v[184:187], v[56:59]
	v_mfma_f32_16x16x32_bf16 v[52:55], v[176:179], v[184:187], v[52:55]
	v_mfma_f32_16x16x32_bf16 v[40:43], v[168:171], v[192:195], v[40:43]
	v_mfma_f32_16x16x32_bf16 v[36:39], v[176:179], v[192:195], v[36:39]
	v_mfma_f32_16x16x32_bf16 v[24:27], v[168:171], v[214:217], v[24:27]
	v_mfma_f32_16x16x32_bf16 v[20:23], v[176:179], v[214:217], v[20:23]
	v_mfma_f32_16x16x32_bf16 v[8:11], v[168:171], v[222:225], v[8:11]
	v_mfma_f32_16x16x32_bf16 v[4:7], v[176:179], v[222:225], v[4:7]
	v_mfma_f32_16x16x32_bf16 v[56:59], v[172:175], v[188:191], v[56:59]
	v_mfma_f32_16x16x32_bf16 v[52:55], v[180:183], v[188:191], v[52:55]
	v_mfma_f32_16x16x32_bf16 v[40:43], v[172:175], v[196:199], v[40:43]
	v_mfma_f32_16x16x32_bf16 v[36:39], v[180:183], v[196:199], v[36:39]
	v_mfma_f32_16x16x32_bf16 v[24:27], v[172:175], v[218:221], v[24:27]
	v_mfma_f32_16x16x32_bf16 v[20:23], v[180:183], v[218:221], v[20:23]
	v_mfma_f32_16x16x32_bf16 v[8:11], v[172:175], v[226:229], v[8:11]
	v_mfma_f32_16x16x32_bf16 v[4:7], v[180:183], v[226:229], v[4:7]
	s_add_i32 s77, s77, 2
	s_add_u32 s70, s70, 0x100
	s_addc_u32 s71, s71, 0
	s_cmp_gt_u32 s77, 13
	s_setprio 0
	s_barrier
	s_cbranch_scc0 .LBB0_216
	s_add_u32 s70, s43, 0xffffff00
	s_addc_u32 s71, s44, -1
	s_andn2_b64 vcc, exec, s[6:7]
	s_cbranch_vccnz .LBB0_219
	v_mov_b32_e32 v4, 0
	s_mov_b32 s20, s28
	s_mov_b32 s18, s30
	s_mov_b64 s[8:9], s[36:37]
	s_mov_b32 s38, s33
	v_mov_b32_e32 v5, v4
	v_mov_b32_e32 v6, v4
	v_mov_b32_e32 v7, v4
	v_mov_b32_e32 v8, v4
	v_mov_b32_e32 v9, v4
	v_mov_b32_e32 v10, v4
	v_mov_b32_e32 v11, v4
	v_mov_b32_e32 v20, v4
	v_mov_b32_e32 v21, v4
	v_mov_b32_e32 v22, v4
	v_mov_b32_e32 v23, v4
	v_mov_b32_e32 v24, v4
	v_mov_b32_e32 v25, v4
	v_mov_b32_e32 v26, v4
	v_mov_b32_e32 v27, v4
	v_mov_b32_e32 v36, v4
	v_mov_b32_e32 v37, v4
	v_mov_b32_e32 v38, v4
	v_mov_b32_e32 v39, v4
	v_mov_b32_e32 v40, v4
	v_mov_b32_e32 v41, v4
	v_mov_b32_e32 v42, v4
	v_mov_b32_e32 v43, v4
	v_mov_b32_e32 v52, v4
	v_mov_b32_e32 v53, v4
	v_mov_b32_e32 v54, v4
	v_mov_b32_e32 v55, v4
	v_mov_b32_e32 v56, v4
	v_mov_b32_e32 v57, v4
	v_mov_b32_e32 v58, v4
	v_mov_b32_e32 v59, v4
	v_mov_b32_e32 v12, v4
	v_mov_b32_e32 v13, v4
	v_mov_b32_e32 v14, v4
	v_mov_b32_e32 v15, v4
	v_mov_b32_e32 v16, v4
	v_mov_b32_e32 v17, v4
	v_mov_b32_e32 v18, v4
	v_mov_b32_e32 v19, v4
	v_mov_b32_e32 v28, v4
	v_mov_b32_e32 v29, v4
	v_mov_b32_e32 v30, v4
	v_mov_b32_e32 v31, v4
	v_mov_b32_e32 v32, v4
	v_mov_b32_e32 v33, v4
	v_mov_b32_e32 v34, v4
	v_mov_b32_e32 v35, v4
	v_mov_b32_e32 v44, v4
	v_mov_b32_e32 v45, v4
	v_mov_b32_e32 v46, v4
	v_mov_b32_e32 v47, v4
	v_mov_b32_e32 v48, v4
	v_mov_b32_e32 v49, v4
	v_mov_b32_e32 v50, v4
	v_mov_b32_e32 v51, v4
	v_mov_b32_e32 v60, v4
	v_mov_b32_e32 v61, v4
	v_mov_b32_e32 v62, v4
	v_mov_b32_e32 v63, v4
	v_mov_b32_e32 v68, v4
	v_mov_b32_e32 v69, v4
	v_mov_b32_e32 v70, v4
	v_mov_b32_e32 v71, v4
	v_mov_b32_e32 v80, v4
	v_mov_b32_e32 v81, v4
	v_mov_b32_e32 v82, v4
	v_mov_b32_e32 v83, v4
	v_mov_b32_e32 v88, v4
	v_mov_b32_e32 v89, v4
	v_mov_b32_e32 v90, v4
	v_mov_b32_e32 v91, v4
	v_mov_b32_e32 v120, v4
	v_mov_b32_e32 v121, v4
	v_mov_b32_e32 v122, v4
	v_mov_b32_e32 v123, v4
	v_mov_b32_e32 v128, v4
	v_mov_b32_e32 v129, v4
	v_mov_b32_e32 v130, v4
	v_mov_b32_e32 v131, v4
	v_mov_b32_e32 v108, v4
	v_mov_b32_e32 v109, v4
	v_mov_b32_e32 v110, v4
	v_mov_b32_e32 v111, v4
	v_mov_b32_e32 v104, v4
	v_mov_b32_e32 v105, v4
	v_mov_b32_e32 v106, v4
	v_mov_b32_e32 v107, v4
	v_mov_b32_e32 v84, v4
	v_mov_b32_e32 v85, v4
	v_mov_b32_e32 v86, v4
	v_mov_b32_e32 v87, v4
	v_mov_b32_e32 v76, v4
	v_mov_b32_e32 v77, v4
	v_mov_b32_e32 v78, v4
	v_mov_b32_e32 v79, v4
	v_mov_b32_e32 v100, v4
	v_mov_b32_e32 v101, v4
	v_mov_b32_e32 v102, v4
	v_mov_b32_e32 v103, v4
	v_mov_b32_e32 v112, v4
	v_mov_b32_e32 v113, v4
	v_mov_b32_e32 v114, v4
	v_mov_b32_e32 v115, v4
	v_mov_b32_e32 v124, v4
	v_mov_b32_e32 v125, v4
	v_mov_b32_e32 v126, v4
	v_mov_b32_e32 v127, v4
	v_mov_b32_e32 v116, v4
	v_mov_b32_e32 v117, v4
	v_mov_b32_e32 v118, v4
	v_mov_b32_e32 v119, v4
	v_mov_b32_e32 v96, v4
	v_mov_b32_e32 v97, v4
	v_mov_b32_e32 v98, v4
	v_mov_b32_e32 v99, v4
	v_mov_b32_e32 v92, v4
	v_mov_b32_e32 v93, v4
	v_mov_b32_e32 v94, v4
	v_mov_b32_e32 v95, v4
	v_mov_b32_e32 v72, v4
	v_mov_b32_e32 v73, v4
	v_mov_b32_e32 v74, v4
	v_mov_b32_e32 v75, v4
	v_mov_b32_e32 v64, v4
	v_mov_b32_e32 v65, v4
	v_mov_b32_e32 v66, v4
	v_mov_b32_e32 v67, v4
	s_mov_b32 s83, 0x18000
	s_mov_b32 s86, 0x3fb8aa3b
	s_andn2_b64 vcc, exec, s[4:5]
	s_cbranch_vccnz .LBB0_220
	s_branch .LBB0_221

; #define PG8_STAGE(bufoff, gbase, voff) do { _Pragma("unroll") for (int _i = 0; _i < 2; ++_i) \
;         __builtin_amdgcn_global_load_lds((const unsigned*)((const char*)(gbase) + (voff)[_i]), (LAS unsigned*)(lds + (bufoff) + ldsw + _i * 8192), 16, 0, 0); } while (0)
; #define PG8_LDA(dst, b, h) do { _Pragma("unroll") for (int m = 0; m < 4; ++m) _Pragma("unroll") for (int k = 0; k < 2; ++k) dst[m][k] = *(const LAS bf16x8*)(lds + PG8_SA(b, h) + aoff + m * 2048 + k * 1024); } while (0)
; #define PG8_LDB(dst, b, h) do { _Pragma("unroll") for (int n = 0; n < 2; ++n) _Pragma("unroll") for (int k = 0; k < 2; ++k) dst[n][k] = *(const LAS bf16x8*)(lds + PG8_SB(b, h) + boff + n * 2048 + k * 1024); } while (0)
; #define PG8_MMA(ai, bj, At, Bt) do { __builtin_amdgcn_s_setprio(1); _Pragma("unroll") for (int m = 0; m < 4; ++m) _Pragma("unroll") for (int n = 0; n < 2; ++n) _Pragma("unroll") for (int k = 0; k < 2; ++k) \
;         acc[ai][bj][m][n] = __builtin_amdgcn_mfma_f32_16x16x32_bf16(Bt[n][k], At[m][k], acc[ai][bj][m][n], 0, 0, 0); __builtin_amdgcn_s_setprio(0); } while (0)
; #define PG8_WAIT_V(n) asm volatile("s_waitcnt vmcnt(" #n ")" ::: "memory")
; #define PG8_WAIT_L(n) asm volatile("s_waitcnt lgkmcnt(" #n ")" ::: "memory")
; #define PG8_BAR __builtin_amdgcn_s_barrier()
; #define PG8_SCHED __builtin_amdgcn_sched_barrier(0)
; template <class Epi>
; __device__ __forceinline__ void gemm_phase(LAS unsigned char* lds, const Gemm g, const int G, const int cidx, const Epi& E) {
;     ...
;             const char* a1 = cA + (size_t)(t + 1) * kstep;
;             const char* a2 = last ? nA : cA + (size_t)(t + 2) * kstep; const char* b2 = last ? nB : cB + (size_t)(t + 2) * kstep;
;             const char* a3 = a2 + kstep; const char* b3 = b2 + kstep;
;             PG8_LDB(B0, 0, 0); PG8_LDB(B1, 0, 1); PG8_SCHED; PG8_LDA(At, 0, 0); PG8_STAGE(PG8_SA(1, 1), a1 + hstep, voffA);
;             PG8_WAIT_V(8); PG8_WAIT_L(0); PG8_BAR; PG8_MMA(0, 0, At, B0); PG8_MMA(0, 1, At, B1); PG8_BAR; PG8_SCHED;
;             PG8_LDA(At, 0, 1); PG8_STAGE(PG8_SB(0, 0), b2, voffB); PG8_STAGE(PG8_SB(0, 1), b2 + hstep, voffB); PG8_STAGE(PG8_SA(0, 0), a2, voffA);
.LBB0_450:
	s_add_i32 s83, 0, 0x10000
	v_add_u32_e32 v3, s83, v157
	ds_read_b128 v[132:135], v3
	ds_read_b128 v[140:143], v3 offset:1024
	ds_read_b128 v[160:163], v3 offset:2048
	ds_read_b128 v[164:167], v3 offset:3072
	s_add_i32 s68, 0, 0x14000
	v_add_u32_e32 v3, s68, v157
	ds_read_b128 v[168:171], v3
	ds_read_b128 v[172:175], v3 offset:1024
	ds_read_b128 v[176:179], v3 offset:2048
	ds_read_b128 v[180:183], v3 offset:3072
	v_lshl_add_u64 v[200:201], v[154:155], 0, s[24:25]
	s_add_i32 m0, s71, 0xc000
	ds_read_b128 v[184:187], v159
	ds_read_b128 v[188:191], v159 offset:1024
	ds_read_b128 v[192:195], v159 offset:2048
	ds_read_b128 v[196:199], v159 offset:3072
	ds_read_b128 v[214:217], v159 offset:4096
	ds_read_b128 v[218:221], v159 offset:5120
	ds_read_b128 v[222:225], v159 offset:6144
	ds_read_b128 v[226:229], v159 offset:7168
	s_add_u32 s26, s10, s24
	s_addc_u32 s27, s11, s25
	s_add_u32 s26, s26, 0x100
	s_addc_u32 s27, s27, 0
	s_add_u32 s68, s43, s24
	s_addc_u32 s77, s44, s25
	s_cmpk_eq_i32 s24, 0x1500
	s_cselect_b32 s29, s21, s27
	s_cselect_b32 s28, s20, s26
	s_cselect_b32 s27, s9, s77
	s_cselect_b32 s26, s8, s68
	s_add_i32 s68, 0, 0x14000
	global_load_lds_dwordx4 v[200:201], off
	v_lshl_add_u64 v[200:201], v[0:1], 0, s[24:25]
	s_add_i32 m0, s71, 0xe000
	s_nop 0
	global_load_lds_dwordx4 v[200:201], off
	s_waitcnt vmcnt(8)
	s_waitcnt lgkmcnt(0)
	s_barrier
	s_setprio 1
	s_waitcnt lgkmcnt(0)
	v_mfma_f32_16x16x32_bf16 v[100:103], v[132:135], v[184:187], v[100:103]
	v_mfma_f32_16x16x32_bf16 v[108:111], v[160:163], v[184:187], v[108:111]
	v_mfma_f32_16x16x32_bf16 v[120:123], v[132:135], v[192:195], v[120:123]
	v_mfma_f32_16x16x32_bf16 v[128:131], v[160:163], v[192:195], v[128:131]
	v_mfma_f32_16x16x32_bf16 v[96:99], v[132:135], v[214:217], v[96:99]
	v_mfma_f32_16x16x32_bf16 v[92:95], v[160:163], v[214:217], v[92:95]
	v_mfma_f32_16x16x32_bf16 v[80:83], v[132:135], v[222:225], v[80:83]
	v_mfma_f32_16x16x32_bf16 v[76:79], v[160:163], v[222:225], v[76:79]
	v_mfma_f32_16x16x32_bf16 v[100:103], v[140:143], v[188:191], v[100:103]
	v_mfma_f32_16x16x32_bf16 v[108:111], v[164:167], v[188:191], v[108:111]
	v_mfma_f32_16x16x32_bf16 v[120:123], v[140:143], v[196:199], v[120:123]
	v_mfma_f32_16x16x32_bf16 v[128:131], v[164:167], v[196:199], v[128:131]
	v_mfma_f32_16x16x32_bf16 v[96:99], v[140:143], v[218:221], v[96:99]
	v_mfma_f32_16x16x32_bf16 v[92:95], v[164:167], v[218:221], v[92:95]
	v_mfma_f32_16x16x32_bf16 v[80:83], v[140:143], v[226:229], v[80:83]
	v_mfma_f32_16x16x32_bf16 v[76:79], v[164:167], v[226:229], v[76:79]
	s_setprio 0
	s_setprio 1
	v_mfma_f32_16x16x32_bf16 v[116:119], v[168:171], v[184:187], v[116:119]
	v_mfma_f32_16x16x32_bf16 v[124:127], v[176:179], v[184:187], v[124:127]
	v_mfma_f32_16x16x32_bf16 v[112:115], v[168:171], v[192:195], v[112:115]
	v_mfma_f32_16x16x32_bf16 v[104:107], v[176:179], v[192:195], v[104:107]
	v_mfma_f32_16x16x32_bf16 v[88:91], v[168:171], v[214:217], v[88:91]
	v_mfma_f32_16x16x32_bf16 v[84:87], v[176:179], v[214:217], v[84:87]
	v_mfma_f32_16x16x32_bf16 v[72:75], v[168:171], v[222:225], v[72:75]
	v_mfma_f32_16x16x32_bf16 v[68:71], v[176:179], v[222:225], v[68:71]
	v_mfma_f32_16x16x32_bf16 v[116:119], v[172:175], v[188:191], v[116:119]
	v_mfma_f32_16x16x32_bf16 v[124:127], v[180:183], v[188:191], v[124:127]
	v_mfma_f32_16x16x32_bf16 v[112:115], v[172:175], v[196:199], v[112:115]
	v_mfma_f32_16x16x32_bf16 v[104:107], v[180:183], v[196:199], v[104:107]
	v_mfma_f32_16x16x32_bf16 v[88:91], v[172:175], v[218:221], v[88:91]
	v_mfma_f32_16x16x32_bf16 v[84:87], v[180:183], v[218:221], v[84:87]
	v_mfma_f32_16x16x32_bf16 v[72:75], v[172:175], v[226:229], v[72:75]
	v_mfma_f32_16x16x32_bf16 v[68:71], v[180:183], v[226:229], v[68:71]
	s_setprio 0
	s_barrier
	s_add_i32 s77, s83, s70
	v_lshl_add_u64 v[200:201], s[26:27], 0, v[146:147]
	s_mov_b32 m0, s77
	ds_read_b128 v[184:187], v159 offset:16384
	ds_read_b128 v[188:191], v159 offset:17408
	ds_read_b128 v[192:195], v159 offset:18432
	ds_read_b128 v[196:199], v159 offset:19456
	ds_read_b128 v[214:217], v159 offset:20480
	ds_read_b128 v[218:221], v159 offset:21504
	ds_read_b128 v[222:225], v159 offset:22528
	ds_read_b128 v[226:229], v159 offset:23552
	global_load_lds_dwordx4 v[200:201], off
	s_add_i32 m0, s77, 0x2000
	s_add_u32 s86, s26, 0xb0000
	v_lshl_add_u64 v[230:231], s[26:27], 0, v[148:149]
	s_addc_u32 s87, s27, 0
	s_add_i32 s68, s68, s70
	global_load_lds_dwordx4 v[230:231], off
	v_lshl_add_u64 v[232:233], s[86:87], 0, v[146:147]
	s_mov_b32 m0, s68
	v_lshl_add_u64 v[234:235], s[28:29], 0, v[148:149]
	global_load_lds_dwordx4 v[232:233], off
	v_lshl_add_u64 v[232:233], s[86:87], 0, v[148:149]
	s_add_i32 m0, s68, 0x2000
	s_nop 0
	global_load_lds_dwordx4 v[232:233], off
	v_lshl_add_u64 v[232:233], s[28:29], 0, v[146:147]
	s_mov_b32 m0, s71
	s_nop 0
	global_load_lds_dwordx4 v[232:233], off
	s_mov_b32 m0, s72
	s_nop 0
	global_load_lds_dwordx4 v[234:235], off
	s_waitcnt vmcnt(8)
	s_waitcnt lgkmcnt(0)
	s_barrier
; #define PG8_STAGE(bufoff, gbase, voff) do { _Pragma("unroll") for (int _i = 0; _i < 2; ++_i) \
;         __builtin_amdgcn_global_load_lds((const unsigned*)((const char*)(gbase) + (voff)[_i]), (LAS unsigned*)(lds + (bufoff) + ldsw + _i * 8192), 16, 0, 0); } while (0)
; #define PG8_LDA(dst, b, h) do { _Pragma("unroll") for (int m = 0; m < 4; ++m) _Pragma("unroll") for (int k = 0; k < 2; ++k) dst[m][k] = *(const LAS bf16x8*)(lds + PG8_SA(b, h) + aoff + m * 2048 + k * 1024); } while (0)
; #define PG8_LDB(dst, b, h) do { _Pragma("unroll") for (int n = 0; n < 2; ++n) _Pragma("unroll") for (int k = 0; k < 2; ++k) dst[n][k] = *(const LAS bf16x8*)(lds + PG8_SB(b, h) + boff + n * 2048 + k * 1024); } while (0)
; #define PG8_MMA(ai, bj, At, Bt) do { __builtin_amdgcn_s_setprio(1); _Pragma("unroll") for (int m = 0; m < 4; ++m) _Pragma("unroll") for (int n = 0; n < 2; ++n) _Pragma("unroll") for (int k = 0; k < 2; ++k) \
;         acc[ai][bj][m][n] = __builtin_amdgcn_mfma_f32_16x16x32_bf16(Bt[n][k], At[m][k], acc[ai][bj][m][n], 0, 0, 0); __builtin_amdgcn_s_setprio(0); } while (0)
; #define PG8_WAIT_V(n) asm volatile("s_waitcnt vmcnt(" #n ")" ::: "memory")
; #define PG8_WAIT_L(n) asm volatile("s_waitcnt lgkmcnt(" #n ")" ::: "memory")
; #define PG8_BAR __builtin_amdgcn_s_barrier()
; #define PG8_SCHED __builtin_amdgcn_sched_barrier(0)
; template <class Epi>
; __device__ __forceinline__ void gemm_phase(LAS unsigned char* lds, const Gemm g, const int G, const int cidx, const Epi& E) {
;     ...
;             PG8_WAIT_V(8); PG8_WAIT_L(0); PG8_BAR; PG8_MMA(0, 0, At, B0); PG8_MMA(0, 1, At, B1); PG8_BAR; PG8_SCHED;
;             PG8_LDA(At, 0, 1); PG8_STAGE(PG8_SB(0, 0), b2, voffB); PG8_STAGE(PG8_SB(0, 1), b2 + hstep, voffB); PG8_STAGE(PG8_SA(0, 0), a2, voffA);
;             PG8_WAIT_V(8); PG8_WAIT_L(0); PG8_BAR; PG8_MMA(1, 0, At, B0); PG8_MMA(1, 1, At, B1); PG8_BAR; PG8_SCHED;
;             PG8_LDB(B0, 1, 0); PG8_LDB(B1, 1, 1); PG8_SCHED; PG8_LDA(At, 1, 0); PG8_STAGE(PG8_SA(0, 1), a2 + hstep, voffA);
;             PG8_WAIT_V(8); PG8_WAIT_L(0); PG8_BAR; PG8_MMA(0, 0, At, B0); PG8_MMA(0, 1, At, B1); PG8_BAR; PG8_SCHED;
;             PG8_LDA(At, 1, 1); PG8_STAGE(PG8_SB(1, 0), b3, voffB); PG8_STAGE(PG8_SB(1, 1), b3 + hstep, voffB); PG8_STAGE(PG8_SA(1, 0), a3, voffA);
;             PG8_WAIT_V(8); PG8_WAIT_L(0); PG8_BAR; PG8_MMA(1, 0, At, B0); PG8_MMA(1, 1, At, B1); PG8_BAR; PG8_SCHED;
	s_setprio 1
	s_waitcnt lgkmcnt(0)
	v_mfma_f32_16x16x32_bf16 v[64:67], v[132:135], v[184:187], v[64:67]
	v_mfma_f32_16x16x32_bf16 v[60:63], v[160:163], v[184:187], v[60:63]
	v_mfma_f32_16x16x32_bf16 v[48:51], v[132:135], v[192:195], v[48:51]
	v_mfma_f32_16x16x32_bf16 v[44:47], v[160:163], v[192:195], v[44:47]
	v_mfma_f32_16x16x32_bf16 v[32:35], v[132:135], v[214:217], v[32:35]
	v_mfma_f32_16x16x32_bf16 v[28:31], v[160:163], v[214:217], v[28:31]
	v_mfma_f32_16x16x32_bf16 v[16:19], v[132:135], v[222:225], v[16:19]
	v_mfma_f32_16x16x32_bf16 v[12:15], v[160:163], v[222:225], v[12:15]
	v_mfma_f32_16x16x32_bf16 v[64:67], v[140:143], v[188:191], v[64:67]
	v_mfma_f32_16x16x32_bf16 v[60:63], v[164:167], v[188:191], v[60:63]
	v_mfma_f32_16x16x32_bf16 v[48:51], v[140:143], v[196:199], v[48:51]
	v_mfma_f32_16x16x32_bf16 v[44:47], v[164:167], v[196:199], v[44:47]
	v_mfma_f32_16x16x32_bf16 v[32:35], v[140:143], v[218:221], v[32:35]
	v_mfma_f32_16x16x32_bf16 v[28:31], v[164:167], v[218:221], v[28:31]
	v_mfma_f32_16x16x32_bf16 v[16:19], v[140:143], v[226:229], v[16:19]
	v_mfma_f32_16x16x32_bf16 v[12:15], v[164:167], v[226:229], v[12:15]
	s_setprio 0
	s_setprio 1
	v_mfma_f32_16x16x32_bf16 v[56:59], v[168:171], v[184:187], v[56:59]
	v_mfma_f32_16x16x32_bf16 v[52:55], v[176:179], v[184:187], v[52:55]
	v_mfma_f32_16x16x32_bf16 v[40:43], v[168:171], v[192:195], v[40:43]
	v_mfma_f32_16x16x32_bf16 v[36:39], v[176:179], v[192:195], v[36:39]
	v_mfma_f32_16x16x32_bf16 v[24:27], v[168:171], v[214:217], v[24:27]
	v_mfma_f32_16x16x32_bf16 v[20:23], v[176:179], v[214:217], v[20:23]
	v_mfma_f32_16x16x32_bf16 v[8:11], v[168:171], v[222:225], v[8:11]
	v_mfma_f32_16x16x32_bf16 v[4:7], v[176:179], v[222:225], v[4:7]
	v_mfma_f32_16x16x32_bf16 v[56:59], v[172:175], v[188:191], v[56:59]
	v_mfma_f32_16x16x32_bf16 v[52:55], v[180:183], v[188:191], v[52:55]
	v_mfma_f32_16x16x32_bf16 v[40:43], v[172:175], v[196:199], v[40:43]
	v_mfma_f32_16x16x32_bf16 v[36:39], v[180:183], v[196:199], v[36:39]
	v_mfma_f32_16x16x32_bf16 v[24:27], v[172:175], v[218:221], v[24:27]
	v_mfma_f32_16x16x32_bf16 v[20:23], v[180:183], v[218:221], v[20:23]
	v_mfma_f32_16x16x32_bf16 v[8:11], v[172:175], v[226:229], v[8:11]
	v_mfma_f32_16x16x32_bf16 v[4:7], v[180:183], v[226:229], v[4:7]
	s_setprio 0
	s_barrier
	s_add_i32 s68, 0, 0x18000
	v_add_u32_e32 v3, s68, v157
	s_add_i32 s77, 0, 0x1c000
	ds_read_b128 v[132:135], v3
	ds_read_b128 v[140:143], v3 offset:1024
	ds_read_b128 v[160:163], v3 offset:2048
	ds_read_b128 v[164:167], v3 offset:3072
	v_add_u32_e32 v3, s77, v157
	ds_read_b128 v[168:171], v3
	ds_read_b128 v[172:175], v3 offset:1024
	ds_read_b128 v[176:179], v3 offset:2048
	ds_read_b128 v[180:183], v3 offset:3072
	s_add_u32 s28, s28, 0xb0000
	s_addc_u32 s29, s29, 0
	s_mov_b32 m0, s73
	v_lshl_add_u64 v[236:237], s[28:29], 0, v[146:147]
	ds_read_b128 v[184:187], v159 offset:32768
	ds_read_b128 v[188:191], v159 offset:33792
	ds_read_b128 v[192:195], v159 offset:34816
	ds_read_b128 v[196:199], v159 offset:35840
	ds_read_b128 v[214:217], v159 offset:36864
	ds_read_b128 v[218:221], v159 offset:37888
	ds_read_b128 v[222:225], v159 offset:38912
	ds_read_b128 v[226:229], v159 offset:39936
	global_load_lds_dwordx4 v[236:237], off
	v_lshl_add_u64 v[236:237], s[28:29], 0, v[148:149]
	s_mov_b32 m0, s74
	s_nop 0
	global_load_lds_dwordx4 v[236:237], off
	s_waitcnt vmcnt(8)
	s_waitcnt lgkmcnt(0)
	s_barrier
	s_setprio 1
	s_waitcnt lgkmcnt(0)
	v_mfma_f32_16x16x32_bf16 v[100:103], v[132:135], v[184:187], v[100:103]
	v_mfma_f32_16x16x32_bf16 v[108:111], v[160:163], v[184:187], v[108:111]
	v_mfma_f32_16x16x32_bf16 v[120:123], v[132:135], v[192:195], v[120:123]
	v_mfma_f32_16x16x32_bf16 v[128:131], v[160:163], v[192:195], v[128:131]
	v_mfma_f32_16x16x32_bf16 v[96:99], v[132:135], v[214:217], v[96:99]
	v_mfma_f32_16x16x32_bf16 v[92:95], v[160:163], v[214:217], v[92:95]
	v_mfma_f32_16x16x32_bf16 v[80:83], v[132:135], v[222:225], v[80:83]
	v_mfma_f32_16x16x32_bf16 v[76:79], v[160:163], v[222:225], v[76:79]
	v_mfma_f32_16x16x32_bf16 v[100:103], v[140:143], v[188:191], v[100:103]
	v_mfma_f32_16x16x32_bf16 v[108:111], v[164:167], v[188:191], v[108:111]
	v_mfma_f32_16x16x32_bf16 v[120:123], v[140:143], v[196:199], v[120:123]
	v_mfma_f32_16x16x32_bf16 v[128:131], v[164:167], v[196:199], v[128:131]
	v_mfma_f32_16x16x32_bf16 v[96:99], v[140:143], v[218:221], v[96:99]
	v_mfma_f32_16x16x32_bf16 v[92:95], v[164:167], v[218:221], v[92:95]
	v_mfma_f32_16x16x32_bf16 v[80:83], v[140:143], v[226:229], v[80:83]
	v_mfma_f32_16x16x32_bf16 v[76:79], v[164:167], v[226:229], v[76:79]
	s_setprio 0
	s_setprio 1
	v_mfma_f32_16x16x32_bf16 v[116:119], v[168:171], v[184:187], v[116:119]
	v_mfma_f32_16x16x32_bf16 v[124:127], v[176:179], v[184:187], v[124:127]
	v_mfma_f32_16x16x32_bf16 v[112:115], v[168:171], v[192:195], v[112:115]
	v_mfma_f32_16x16x32_bf16 v[104:107], v[176:179], v[192:195], v[104:107]
	v_mfma_f32_16x16x32_bf16 v[88:91], v[168:171], v[214:217], v[88:91]
	v_mfma_f32_16x16x32_bf16 v[84:87], v[176:179], v[214:217], v[84:87]
	v_mfma_f32_16x16x32_bf16 v[72:75], v[168:171], v[222:225], v[72:75]
	v_mfma_f32_16x16x32_bf16 v[68:71], v[176:179], v[222:225], v[68:71]
	v_mfma_f32_16x16x32_bf16 v[116:119], v[172:175], v[188:191], v[116:119]
	v_mfma_f32_16x16x32_bf16 v[124:127], v[180:183], v[188:191], v[124:127]
	v_mfma_f32_16x16x32_bf16 v[112:115], v[172:175], v[196:199], v[112:115]
	v_mfma_f32_16x16x32_bf16 v[104:107], v[180:183], v[196:199], v[104:107]
	v_mfma_f32_16x16x32_bf16 v[88:91], v[172:175], v[218:221], v[88:91]
	v_mfma_f32_16x16x32_bf16 v[84:87], v[180:183], v[218:221], v[84:87]
	v_mfma_f32_16x16x32_bf16 v[72:75], v[172:175], v[226:229], v[72:75]
	v_mfma_f32_16x16x32_bf16 v[68:71], v[180:183], v[226:229], v[68:71]
	s_setprio 0
	s_barrier
; #define PG8_STAGE(bufoff, gbase, voff) do { _Pragma("unroll") for (int _i = 0; _i < 2; ++_i) \
;         __builtin_amdgcn_global_load_lds((const unsigned*)((const char*)(gbase) + (voff)[_i]), (LAS unsigned*)(lds + (bufoff) + ldsw + _i * 8192), 16, 0, 0); } while (0)
; #define PG8_LDA(dst, b, h) do { _Pragma("unroll") for (int m = 0; m < 4; ++m) _Pragma("unroll") for (int k = 0; k < 2; ++k) dst[m][k] = *(const LAS bf16x8*)(lds + PG8_SA(b, h) + aoff + m * 2048 + k * 1024); } while (0)
; #define PG8_LDB(dst, b, h) do { _Pragma("unroll") for (int n = 0; n < 2; ++n) _Pragma("unroll") for (int k = 0; k < 2; ++k) dst[n][k] = *(const LAS bf16x8*)(lds + PG8_SB(b, h) + boff + n * 2048 + k * 1024); } while (0)
; #define PG8_MMA(ai, bj, At, Bt) do { __builtin_amdgcn_s_setprio(1); _Pragma("unroll") for (int m = 0; m < 4; ++m) _Pragma("unroll") for (int n = 0; n < 2; ++n) _Pragma("unroll") for (int k = 0; k < 2; ++k) \
;         acc[ai][bj][m][n] = __builtin_amdgcn_mfma_f32_16x16x32_bf16(Bt[n][k], At[m][k], acc[ai][bj][m][n], 0, 0, 0); __builtin_amdgcn_s_setprio(0); } while (0)
; #define PG8_WAIT_V(n) asm volatile("s_waitcnt vmcnt(" #n ")" ::: "memory")
; template <class Epi>
; __device__ __forceinline__ void gemm_phase(LAS unsigned char* lds, const Gemm g, const int G, const int cidx, const Epi& E) {
;     ...
;             PG8_WAIT_V(8); PG8_WAIT_L(0); PG8_BAR; PG8_MMA(1, 0, At, B0); PG8_MMA(1, 1, At, B1); PG8_BAR; PG8_SCHED;
;             PG8_LDB(B0, 1, 0); PG8_LDB(B1, 1, 1); PG8_SCHED; PG8_LDA(At, 1, 0); PG8_STAGE(PG8_SA(0, 1), a2 + hstep, voffA);
;             PG8_WAIT_V(8); PG8_WAIT_L(0); PG8_BAR; PG8_MMA(0, 0, At, B0); PG8_MMA(0, 1, At, B1); PG8_BAR; PG8_SCHED;
;             PG8_LDA(At, 1, 1); PG8_STAGE(PG8_SB(1, 0), b3, voffB); PG8_STAGE(PG8_SB(1, 1), b3 + hstep, voffB); PG8_STAGE(PG8_SA(1, 0), a3, voffA);
;             PG8_WAIT_V(8); PG8_WAIT_L(0); PG8_BAR; PG8_MMA(1, 0, At, B0); PG8_MMA(1, 1, At, B1); PG8_BAR; PG8_SCHED;
;         }
;         if constexpr (!Epi::AFTER_DRAIN) E(acc, cur, wr, wc, fr, fq);
;         if (!has_next) break;
; #pragma unroll
;         for (int a = 0; a < 2; ++a)
; #pragma unroll
;             for (int b = 0; b < 2; ++b)
; #pragma unroll
;                 for (int m = 0; m < 4; ++m)
; #pragma unroll
;                     for (int n = 0; n < 2; ++n) acc[a][b][m][n] = ZERO4;
;         cur = nxt; cA = nA; cB = nB; ++ui;
	s_add_i32 s28, s68, s70
	v_lshl_add_u64 v[200:201], v[200:201], 0, s[46:47]
	s_mov_b32 m0, s28
	ds_read_b128 v[184:187], v159 offset:49152
	ds_read_b128 v[188:191], v159 offset:50176
	ds_read_b128 v[192:195], v159 offset:51200
	ds_read_b128 v[196:199], v159 offset:52224
	ds_read_b128 v[214:217], v159 offset:53248
	ds_read_b128 v[218:221], v159 offset:54272
	ds_read_b128 v[222:225], v159 offset:55296
	ds_read_b128 v[226:229], v159 offset:56320
	global_load_lds_dwordx4 v[200:201], off
	s_add_i32 m0, s28, 0x2000
	s_add_u32 s26, s26, 0xb0080
	v_lshl_add_u64 v[200:201], v[230:231], 0, s[46:47]
	s_addc_u32 s27, s27, 0
	s_add_i32 s28, s77, s70
	global_load_lds_dwordx4 v[200:201], off
	v_lshl_add_u64 v[200:201], s[26:27], 0, v[146:147]
	s_mov_b32 m0, s28
	s_nop 0
	global_load_lds_dwordx4 v[200:201], off
	v_lshl_add_u64 v[200:201], s[26:27], 0, v[148:149]
	s_add_i32 m0, s28, 0x2000
	s_nop 0
	global_load_lds_dwordx4 v[200:201], off
	v_lshl_add_u64 v[200:201], v[232:233], 0, s[46:47]
	s_mov_b32 m0, s75
	s_nop 0
	global_load_lds_dwordx4 v[200:201], off
	v_lshl_add_u64 v[200:201], v[234:235], 0, s[46:47]
	s_mov_b32 m0, s76
	s_nop 0
	global_load_lds_dwordx4 v[200:201], off
	s_waitcnt vmcnt(8)
	s_waitcnt lgkmcnt(0)
	s_barrier
	s_setprio 1
	s_waitcnt lgkmcnt(0)
	v_mfma_f32_16x16x32_bf16 v[64:67], v[132:135], v[184:187], v[64:67]
	v_mfma_f32_16x16x32_bf16 v[60:63], v[160:163], v[184:187], v[60:63]
	v_mfma_f32_16x16x32_bf16 v[48:51], v[132:135], v[192:195], v[48:51]
	v_mfma_f32_16x16x32_bf16 v[44:47], v[160:163], v[192:195], v[44:47]
	v_mfma_f32_16x16x32_bf16 v[32:35], v[132:135], v[214:217], v[32:35]
	v_mfma_f32_16x16x32_bf16 v[28:31], v[160:163], v[214:217], v[28:31]
	v_mfma_f32_16x16x32_bf16 v[16:19], v[132:135], v[222:225], v[16:19]
	v_mfma_f32_16x16x32_bf16 v[12:15], v[160:163], v[222:225], v[12:15]
	v_mfma_f32_16x16x32_bf16 v[64:67], v[140:143], v[188:191], v[64:67]
	v_mfma_f32_16x16x32_bf16 v[60:63], v[164:167], v[188:191], v[60:63]
	v_mfma_f32_16x16x32_bf16 v[48:51], v[140:143], v[196:199], v[48:51]
	v_mfma_f32_16x16x32_bf16 v[44:47], v[164:167], v[196:199], v[44:47]
	v_mfma_f32_16x16x32_bf16 v[32:35], v[140:143], v[218:221], v[32:35]
	v_mfma_f32_16x16x32_bf16 v[28:31], v[164:167], v[218:221], v[28:31]
	v_mfma_f32_16x16x32_bf16 v[16:19], v[140:143], v[226:229], v[16:19]
	v_mfma_f32_16x16x32_bf16 v[12:15], v[164:167], v[226:229], v[12:15]
	s_setprio 0
	s_setprio 1
	v_mfma_f32_16x16x32_bf16 v[56:59], v[168:171], v[184:187], v[56:59]
	v_mfma_f32_16x16x32_bf16 v[52:55], v[176:179], v[184:187], v[52:55]
	v_mfma_f32_16x16x32_bf16 v[40:43], v[168:171], v[192:195], v[40:43]
	v_mfma_f32_16x16x32_bf16 v[36:39], v[176:179], v[192:195], v[36:39]
	v_mfma_f32_16x16x32_bf16 v[24:27], v[168:171], v[214:217], v[24:27]
	v_mfma_f32_16x16x32_bf16 v[20:23], v[176:179], v[214:217], v[20:23]
	v_mfma_f32_16x16x32_bf16 v[8:11], v[168:171], v[222:225], v[8:11]
	v_mfma_f32_16x16x32_bf16 v[4:7], v[176:179], v[222:225], v[4:7]
	v_mfma_f32_16x16x32_bf16 v[56:59], v[172:175], v[188:191], v[56:59]
	v_mfma_f32_16x16x32_bf16 v[52:55], v[180:183], v[188:191], v[52:55]
	v_mfma_f32_16x16x32_bf16 v[40:43], v[172:175], v[196:199], v[40:43]
	v_mfma_f32_16x16x32_bf16 v[36:39], v[180:183], v[196:199], v[36:39]
	v_mfma_f32_16x16x32_bf16 v[24:27], v[172:175], v[218:221], v[24:27]
	v_mfma_f32_16x16x32_bf16 v[20:23], v[180:183], v[218:221], v[20:23]
	v_mfma_f32_16x16x32_bf16 v[8:11], v[172:175], v[226:229], v[8:11]
	v_mfma_f32_16x16x32_bf16 v[4:7], v[180:183], v[226:229], v[4:7]
	s_add_i32 s45, s45, 2
	s_add_u32 s24, s24, 0x100
	s_addc_u32 s25, s25, 0
	s_cmp_gt_u32 s45, 41
	s_setprio 0
	s_barrier
	s_cbranch_scc0 .LBB0_450
	s_add_u32 s24, s43, 0xffffff00
	s_addc_u32 s25, s44, -1
	s_and_b64 vcc, exec, s[6:7]
	s_cbranch_vccnz .LBB0_453
	v_mov_b32_e32 v4, 0
	s_mov_b32 s14, s84
	s_mov_b32 s35, s88
	s_mov_b64 s[10:11], s[20:21]
	s_mov_b32 s79, s33
	v_mov_b32_e32 v5, v4
	v_mov_b32_e32 v6, v4
	v_mov_b32_e32 v7, v4
	v_mov_b32_e32 v8, v4
	v_mov_b32_e32 v9, v4
	v_mov_b32_e32 v10, v4
	v_mov_b32_e32 v11, v4
	v_mov_b32_e32 v20, v4
	v_mov_b32_e32 v21, v4
	v_mov_b32_e32 v22, v4
	v_mov_b32_e32 v23, v4
	v_mov_b32_e32 v24, v4
	v_mov_b32_e32 v25, v4
	v_mov_b32_e32 v26, v4
	v_mov_b32_e32 v27, v4
	v_mov_b32_e32 v36, v4
	v_mov_b32_e32 v37, v4
	v_mov_b32_e32 v38, v4
	v_mov_b32_e32 v39, v4
	v_mov_b32_e32 v40, v4
	v_mov_b32_e32 v41, v4
	v_mov_b32_e32 v42, v4
	v_mov_b32_e32 v43, v4
	v_mov_b32_e32 v52, v4
	v_mov_b32_e32 v53, v4
	v_mov_b32_e32 v54, v4
	v_mov_b32_e32 v55, v4
	v_mov_b32_e32 v56, v4
	v_mov_b32_e32 v57, v4
	v_mov_b32_e32 v58, v4
	v_mov_b32_e32 v59, v4
	v_mov_b32_e32 v12, v4
	v_mov_b32_e32 v13, v4
	v_mov_b32_e32 v14, v4
	v_mov_b32_e32 v15, v4
	v_mov_b32_e32 v16, v4
	v_mov_b32_e32 v17, v4
	v_mov_b32_e32 v18, v4
	v_mov_b32_e32 v19, v4
	v_mov_b32_e32 v28, v4
	v_mov_b32_e32 v29, v4
	v_mov_b32_e32 v30, v4
	v_mov_b32_e32 v31, v4
	v_mov_b32_e32 v32, v4
	v_mov_b32_e32 v33, v4
	v_mov_b32_e32 v34, v4
	v_mov_b32_e32 v35, v4
	v_mov_b32_e32 v44, v4
	v_mov_b32_e32 v45, v4
	v_mov_b32_e32 v46, v4
	v_mov_b32_e32 v47, v4
	v_mov_b32_e32 v48, v4
	v_mov_b32_e32 v49, v4
	v_mov_b32_e32 v50, v4
	v_mov_b32_e32 v51, v4
	v_mov_b32_e32 v60, v4
	v_mov_b32_e32 v61, v4
	v_mov_b32_e32 v62, v4
	v_mov_b32_e32 v63, v4
	v_mov_b32_e32 v64, v4
	v_mov_b32_e32 v65, v4
	v_mov_b32_e32 v66, v4
	v_mov_b32_e32 v67, v4
	v_mov_b32_e32 v68, v4
	v_mov_b32_e32 v69, v4
	v_mov_b32_e32 v70, v4
	v_mov_b32_e32 v71, v4
	v_mov_b32_e32 v72, v4
	v_mov_b32_e32 v73, v4
	v_mov_b32_e32 v74, v4
	v_mov_b32_e32 v75, v4
	v_mov_b32_e32 v84, v4
	v_mov_b32_e32 v85, v4
	v_mov_b32_e32 v86, v4
	v_mov_b32_e32 v87, v4
	v_mov_b32_e32 v88, v4
	v_mov_b32_e32 v89, v4
	v_mov_b32_e32 v90, v4
	v_mov_b32_e32 v91, v4
	v_mov_b32_e32 v104, v4
	v_mov_b32_e32 v105, v4
	v_mov_b32_e32 v106, v4
	v_mov_b32_e32 v107, v4
	v_mov_b32_e32 v112, v4
	v_mov_b32_e32 v113, v4
	v_mov_b32_e32 v114, v4
	v_mov_b32_e32 v115, v4
	v_mov_b32_e32 v124, v4
	v_mov_b32_e32 v125, v4
	v_mov_b32_e32 v126, v4
	v_mov_b32_e32 v127, v4
	v_mov_b32_e32 v116, v4
	v_mov_b32_e32 v117, v4
	v_mov_b32_e32 v118, v4
	v_mov_b32_e32 v119, v4
	v_mov_b32_e32 v76, v4
	v_mov_b32_e32 v77, v4
	v_mov_b32_e32 v78, v4
	v_mov_b32_e32 v79, v4
	v_mov_b32_e32 v80, v4
	v_mov_b32_e32 v81, v4
	v_mov_b32_e32 v82, v4
	v_mov_b32_e32 v83, v4
	v_mov_b32_e32 v92, v4
	v_mov_b32_e32 v93, v4
	v_mov_b32_e32 v94, v4
	v_mov_b32_e32 v95, v4
	v_mov_b32_e32 v96, v4
	v_mov_b32_e32 v97, v4
	v_mov_b32_e32 v98, v4
	v_mov_b32_e32 v99, v4
	v_mov_b32_e32 v128, v4
	v_mov_b32_e32 v129, v4
	v_mov_b32_e32 v130, v4
	v_mov_b32_e32 v131, v4
	v_mov_b32_e32 v120, v4
	v_mov_b32_e32 v121, v4
	v_mov_b32_e32 v122, v4
	v_mov_b32_e32 v123, v4
	v_mov_b32_e32 v108, v4
	v_mov_b32_e32 v109, v4
	v_mov_b32_e32 v110, v4
	v_mov_b32_e32 v111, v4
	v_mov_b32_e32 v100, v4
	v_mov_b32_e32 v101, v4
	v_mov_b32_e32 v102, v4
	v_mov_b32_e32 v103, v4
	s_mov_b32 s83, 0x18000
	s_mov_b32 s86, 0x3fb8aa3b
	s_andn2_b64 vcc, exec, s[4:5]
	s_cbranch_vccnz .LBB0_454
	s_branch .LBB0_455

; #define PG8_STAGE(bufoff, gbase, voff) do { _Pragma("unroll") for (int _i = 0; _i < 2; ++_i) \
;         __builtin_amdgcn_global_load_lds((const unsigned*)((const char*)(gbase) + (voff)[_i]), (LAS unsigned*)(lds + (bufoff) + ldsw + _i * 8192), 16, 0, 0); } while (0)
; #define PG8_LDA(dst, b, h) do { _Pragma("unroll") for (int m = 0; m < 4; ++m) _Pragma("unroll") for (int k = 0; k < 2; ++k) dst[m][k] = *(const LAS bf16x8*)(lds + PG8_SA(b, h) + aoff + m * 2048 + k * 1024); } while (0)
; #define PG8_LDB(dst, b, h) do { _Pragma("unroll") for (int n = 0; n < 2; ++n) _Pragma("unroll") for (int k = 0; k < 2; ++k) dst[n][k] = *(const LAS bf16x8*)(lds + PG8_SB(b, h) + boff + n * 2048 + k * 1024); } while (0)
; #define PG8_MMA(ai, bj, At, Bt) do { __builtin_amdgcn_s_setprio(1); _Pragma("unroll") for (int m = 0; m < 4; ++m) _Pragma("unroll") for (int n = 0; n < 2; ++n) _Pragma("unroll") for (int k = 0; k < 2; ++k) \
;         acc[ai][bj][m][n] = __builtin_amdgcn_mfma_f32_16x16x32_bf16(Bt[n][k], At[m][k], acc[ai][bj][m][n], 0, 0, 0); __builtin_amdgcn_s_setprio(0); } while (0)
; #define PG8_WAIT_V(n) asm volatile("s_waitcnt vmcnt(" #n ")" ::: "memory")
; #define PG8_WAIT_L(n) asm volatile("s_waitcnt lgkmcnt(" #n ")" ::: "memory")
; #define PG8_BAR __builtin_amdgcn_s_barrier()
; #define PG8_SCHED __builtin_amdgcn_sched_barrier(0)
; template <class Epi>
; __device__ __forceinline__ void gemm_phase(LAS unsigned char* lds, const Gemm g, const int G, const int cidx, const Epi& E) {
;     ...
;             const char* a1 = cA + (size_t)(t + 1) * kstep;
;             const char* a2 = last ? nA : cA + (size_t)(t + 2) * kstep; const char* b2 = last ? nB : cB + (size_t)(t + 2) * kstep;
;             const char* a3 = a2 + kstep; const char* b3 = b2 + kstep;
;             PG8_LDB(B0, 0, 0); PG8_LDB(B1, 0, 1); PG8_SCHED; PG8_LDA(At, 0, 0); PG8_STAGE(PG8_SA(1, 1), a1 + hstep, voffA);
;             PG8_WAIT_V(8); PG8_WAIT_L(0); PG8_BAR; PG8_MMA(0, 0, At, B0); PG8_MMA(0, 1, At, B1); PG8_BAR; PG8_SCHED;
;             PG8_LDA(At, 0, 1); PG8_STAGE(PG8_SB(0, 0), b2, voffB); PG8_STAGE(PG8_SB(0, 1), b2 + hstep, voffB); PG8_STAGE(PG8_SA(0, 0), a2, voffA);
.LBB0_601:
	s_add_i32 s43, 0, 0x10000
	v_add_u32_e32 v132, s43, v145
	ds_read_b128 v[158:161], v132
	ds_read_b128 v[164:167], v132 offset:1024
	ds_read_b128 v[168:171], v132 offset:2048
	ds_read_b128 v[172:175], v132 offset:3072
	s_add_i32 s68, 0, 0x14000
	v_add_u32_e32 v132, s68, v145
	ds_read_b128 v[176:179], v132
	ds_read_b128 v[180:183], v132 offset:1024
	ds_read_b128 v[184:187], v132 offset:2048
	ds_read_b128 v[188:191], v132 offset:3072
	v_lshl_add_u64 v[132:133], s[20:21], 0, v[156:157]
	s_add_i32 m0, s97, 0xc000
	ds_read_b128 v[192:195], v163
	ds_read_b128 v[196:199], v163 offset:1024
	ds_read_b128 v[214:217], v163 offset:2048
	ds_read_b128 v[218:221], v163 offset:3072
	ds_read_b128 v[222:225], v163 offset:4096
	ds_read_b128 v[226:229], v163 offset:5120
	ds_read_b128 v[230:233], v163 offset:6144
	ds_read_b128 v[234:237], v163 offset:7168
	s_add_u32 s24, s20, 0xfffc0080
	s_addc_u32 s25, s21, -1
	s_cmp_eq_u32 s45, 12
	s_cselect_b32 s27, s11, s25
	s_cselect_b32 s26, s19, s24
	s_cselect_b32 s25, s9, s44
	s_cselect_b32 s24, s33, s42
	global_load_lds_dwordx4 v[132:133], off
	v_lshl_add_u64 v[132:133], s[20:21], 0, v[154:155]
	s_add_i32 m0, s97, 0xe000
	s_nop 0
	global_load_lds_dwordx4 v[132:133], off
	s_waitcnt vmcnt(8)
	s_waitcnt lgkmcnt(0)
	s_barrier
	s_setprio 1
	s_waitcnt lgkmcnt(0)
	v_mfma_f32_16x16x32_bf16 v[128:131], v[158:161], v[192:195], v[128:131]
	v_mfma_f32_16x16x32_bf16 v[124:127], v[168:171], v[192:195], v[124:127]
	v_mfma_f32_16x16x32_bf16 v[120:123], v[158:161], v[214:217], v[120:123]
	v_mfma_f32_16x16x32_bf16 v[112:115], v[168:171], v[214:217], v[112:115]
	v_mfma_f32_16x16x32_bf16 v[104:107], v[158:161], v[222:225], v[104:107]
	v_mfma_f32_16x16x32_bf16 v[96:99], v[168:171], v[222:225], v[96:99]
	v_mfma_f32_16x16x32_bf16 v[88:91], v[158:161], v[230:233], v[88:91]
	v_mfma_f32_16x16x32_bf16 v[80:83], v[168:171], v[230:233], v[80:83]
	v_mfma_f32_16x16x32_bf16 v[128:131], v[164:167], v[196:199], v[128:131]
	v_mfma_f32_16x16x32_bf16 v[124:127], v[172:175], v[196:199], v[124:127]
	v_mfma_f32_16x16x32_bf16 v[120:123], v[164:167], v[218:221], v[120:123]
	v_mfma_f32_16x16x32_bf16 v[112:115], v[172:175], v[218:221], v[112:115]
	v_mfma_f32_16x16x32_bf16 v[104:107], v[164:167], v[226:229], v[104:107]
	v_mfma_f32_16x16x32_bf16 v[96:99], v[172:175], v[226:229], v[96:99]
	v_mfma_f32_16x16x32_bf16 v[88:91], v[164:167], v[234:237], v[88:91]
	v_mfma_f32_16x16x32_bf16 v[80:83], v[172:175], v[234:237], v[80:83]
	s_setprio 0
	s_setprio 1
	v_mfma_f32_16x16x32_bf16 v[116:119], v[176:179], v[192:195], v[116:119]
	v_mfma_f32_16x16x32_bf16 v[108:111], v[184:187], v[192:195], v[108:111]
	v_mfma_f32_16x16x32_bf16 v[100:103], v[176:179], v[214:217], v[100:103]
	v_mfma_f32_16x16x32_bf16 v[92:95], v[184:187], v[214:217], v[92:95]
	v_mfma_f32_16x16x32_bf16 v[84:87], v[176:179], v[222:225], v[84:87]
	v_mfma_f32_16x16x32_bf16 v[76:79], v[184:187], v[222:225], v[76:79]
	v_mfma_f32_16x16x32_bf16 v[72:75], v[176:179], v[230:233], v[72:75]
	v_mfma_f32_16x16x32_bf16 v[68:71], v[184:187], v[230:233], v[68:71]
	v_mfma_f32_16x16x32_bf16 v[116:119], v[180:183], v[196:199], v[116:119]
	v_mfma_f32_16x16x32_bf16 v[108:111], v[188:191], v[196:199], v[108:111]
	v_mfma_f32_16x16x32_bf16 v[100:103], v[180:183], v[218:221], v[100:103]
	v_mfma_f32_16x16x32_bf16 v[92:95], v[188:191], v[218:221], v[92:95]
	v_mfma_f32_16x16x32_bf16 v[84:87], v[180:183], v[226:229], v[84:87]
	v_mfma_f32_16x16x32_bf16 v[76:79], v[188:191], v[226:229], v[76:79]
	v_mfma_f32_16x16x32_bf16 v[72:75], v[180:183], v[234:237], v[72:75]
	v_mfma_f32_16x16x32_bf16 v[68:71], v[188:191], v[234:237], v[68:71]
	s_setprio 0
	s_barrier
	s_add_i32 s43, s43, s95
	v_lshl_add_u64 v[132:133], s[24:25], 0, v[148:149]
	s_mov_b32 m0, s43
	ds_read_b128 v[192:195], v163 offset:16384
	ds_read_b128 v[196:199], v163 offset:17408
	ds_read_b128 v[214:217], v163 offset:18432
	ds_read_b128 v[218:221], v163 offset:19456
	ds_read_b128 v[222:225], v163 offset:20480
	ds_read_b128 v[226:229], v163 offset:21504
	ds_read_b128 v[230:233], v163 offset:22528
	ds_read_b128 v[234:237], v163 offset:23552
	global_load_lds_dwordx4 v[132:133], off
	s_add_i32 m0, s43, 0x2000
	s_add_u32 s86, s24, 0x40000
	v_lshl_add_u64 v[134:135], s[24:25], 0, v[0:1]
	s_addc_u32 s87, s25, 0
	s_add_i32 s43, s68, s95
	global_load_lds_dwordx4 v[134:135], off
	v_lshl_add_u64 v[140:141], s[86:87], 0, v[148:149]
	s_mov_b32 m0, s43
	v_lshl_add_u64 v[142:143], s[26:27], 0, v[146:147]
	global_load_lds_dwordx4 v[140:141], off
	v_lshl_add_u64 v[140:141], s[86:87], 0, v[0:1]
	s_add_i32 m0, s43, 0x2000
	s_nop 0
	global_load_lds_dwordx4 v[140:141], off
	v_lshl_add_u64 v[140:141], s[26:27], 0, v[150:151]
	s_mov_b32 m0, s97
	s_nop 0
	global_load_lds_dwordx4 v[140:141], off
	s_mov_b32 m0, s22
	s_nop 0
	global_load_lds_dwordx4 v[142:143], off
	s_waitcnt vmcnt(8)
	s_waitcnt lgkmcnt(0)
	s_barrier
; #define PG8_STAGE(bufoff, gbase, voff) do { _Pragma("unroll") for (int _i = 0; _i < 2; ++_i) \
;         __builtin_amdgcn_global_load_lds((const unsigned*)((const char*)(gbase) + (voff)[_i]), (LAS unsigned*)(lds + (bufoff) + ldsw + _i * 8192), 16, 0, 0); } while (0)
; #define PG8_LDA(dst, b, h) do { _Pragma("unroll") for (int m = 0; m < 4; ++m) _Pragma("unroll") for (int k = 0; k < 2; ++k) dst[m][k] = *(const LAS bf16x8*)(lds + PG8_SA(b, h) + aoff + m * 2048 + k * 1024); } while (0)
; #define PG8_LDB(dst, b, h) do { _Pragma("unroll") for (int n = 0; n < 2; ++n) _Pragma("unroll") for (int k = 0; k < 2; ++k) dst[n][k] = *(const LAS bf16x8*)(lds + PG8_SB(b, h) + boff + n * 2048 + k * 1024); } while (0)
; #define PG8_MMA(ai, bj, At, Bt) do { __builtin_amdgcn_s_setprio(1); _Pragma("unroll") for (int m = 0; m < 4; ++m) _Pragma("unroll") for (int n = 0; n < 2; ++n) _Pragma("unroll") for (int k = 0; k < 2; ++k) \
;         acc[ai][bj][m][n] = __builtin_amdgcn_mfma_f32_16x16x32_bf16(Bt[n][k], At[m][k], acc[ai][bj][m][n], 0, 0, 0); __builtin_amdgcn_s_setprio(0); } while (0)
; #define PG8_WAIT_V(n) asm volatile("s_waitcnt vmcnt(" #n ")" ::: "memory")
; #define PG8_WAIT_L(n) asm volatile("s_waitcnt lgkmcnt(" #n ")" ::: "memory")
; #define PG8_BAR __builtin_amdgcn_s_barrier()
; #define PG8_SCHED __builtin_amdgcn_sched_barrier(0)
; template <class Epi>
; __device__ __forceinline__ void gemm_phase(LAS unsigned char* lds, const Gemm g, const int G, const int cidx, const Epi& E) {
;     ...
;             PG8_WAIT_V(8); PG8_WAIT_L(0); PG8_BAR; PG8_MMA(0, 0, At, B0); PG8_MMA(0, 1, At, B1); PG8_BAR; PG8_SCHED;
;             PG8_LDA(At, 0, 1); PG8_STAGE(PG8_SB(0, 0), b2, voffB); PG8_STAGE(PG8_SB(0, 1), b2 + hstep, voffB); PG8_STAGE(PG8_SA(0, 0), a2, voffA);
;             PG8_WAIT_V(8); PG8_WAIT_L(0); PG8_BAR; PG8_MMA(1, 0, At, B0); PG8_MMA(1, 1, At, B1); PG8_BAR; PG8_SCHED;
;             PG8_LDB(B0, 1, 0); PG8_LDB(B1, 1, 1); PG8_SCHED; PG8_LDA(At, 1, 0); PG8_STAGE(PG8_SA(0, 1), a2 + hstep, voffA);
;             PG8_WAIT_V(8); PG8_WAIT_L(0); PG8_BAR; PG8_MMA(0, 0, At, B0); PG8_MMA(0, 1, At, B1); PG8_BAR; PG8_SCHED;
;             PG8_LDA(At, 1, 1); PG8_STAGE(PG8_SB(1, 0), b3, voffB); PG8_STAGE(PG8_SB(1, 1), b3 + hstep, voffB); PG8_STAGE(PG8_SA(1, 0), a3, voffA);
;             PG8_WAIT_V(8); PG8_WAIT_L(0); PG8_BAR; PG8_MMA(1, 0, At, B0); PG8_MMA(1, 1, At, B1); PG8_BAR; PG8_SCHED;
	s_setprio 1
	s_waitcnt lgkmcnt(0)
	v_mfma_f32_16x16x32_bf16 v[64:67], v[158:161], v[192:195], v[64:67]
	v_mfma_f32_16x16x32_bf16 v[60:63], v[168:171], v[192:195], v[60:63]
	v_mfma_f32_16x16x32_bf16 v[56:59], v[158:161], v[214:217], v[56:59]
	v_mfma_f32_16x16x32_bf16 v[48:51], v[168:171], v[214:217], v[48:51]
	v_mfma_f32_16x16x32_bf16 v[40:43], v[158:161], v[222:225], v[40:43]
	v_mfma_f32_16x16x32_bf16 v[32:35], v[168:171], v[222:225], v[32:35]
	v_mfma_f32_16x16x32_bf16 v[24:27], v[158:161], v[230:233], v[24:27]
	v_mfma_f32_16x16x32_bf16 v[16:19], v[168:171], v[230:233], v[16:19]
	v_mfma_f32_16x16x32_bf16 v[64:67], v[164:167], v[196:199], v[64:67]
	v_mfma_f32_16x16x32_bf16 v[60:63], v[172:175], v[196:199], v[60:63]
	v_mfma_f32_16x16x32_bf16 v[56:59], v[164:167], v[218:221], v[56:59]
	v_mfma_f32_16x16x32_bf16 v[48:51], v[172:175], v[218:221], v[48:51]
	v_mfma_f32_16x16x32_bf16 v[40:43], v[164:167], v[226:229], v[40:43]
	v_mfma_f32_16x16x32_bf16 v[32:35], v[172:175], v[226:229], v[32:35]
	v_mfma_f32_16x16x32_bf16 v[24:27], v[164:167], v[234:237], v[24:27]
	v_mfma_f32_16x16x32_bf16 v[16:19], v[172:175], v[234:237], v[16:19]
	s_setprio 0
	s_setprio 1
	v_mfma_f32_16x16x32_bf16 v[52:55], v[176:179], v[192:195], v[52:55]
	v_mfma_f32_16x16x32_bf16 v[44:47], v[184:187], v[192:195], v[44:47]
	v_mfma_f32_16x16x32_bf16 v[36:39], v[176:179], v[214:217], v[36:39]
	v_mfma_f32_16x16x32_bf16 v[28:31], v[184:187], v[214:217], v[28:31]
	v_mfma_f32_16x16x32_bf16 v[20:23], v[176:179], v[222:225], v[20:23]
	v_mfma_f32_16x16x32_bf16 v[12:15], v[184:187], v[222:225], v[12:15]
	v_mfma_f32_16x16x32_bf16 v[8:11], v[176:179], v[230:233], v[8:11]
	v_mfma_f32_16x16x32_bf16 v[4:7], v[184:187], v[230:233], v[4:7]
	v_mfma_f32_16x16x32_bf16 v[52:55], v[180:183], v[196:199], v[52:55]
	v_mfma_f32_16x16x32_bf16 v[44:47], v[188:191], v[196:199], v[44:47]
	v_mfma_f32_16x16x32_bf16 v[36:39], v[180:183], v[218:221], v[36:39]
	v_mfma_f32_16x16x32_bf16 v[28:31], v[188:191], v[218:221], v[28:31]
	v_mfma_f32_16x16x32_bf16 v[20:23], v[180:183], v[226:229], v[20:23]
	v_mfma_f32_16x16x32_bf16 v[12:15], v[188:191], v[226:229], v[12:15]
	v_mfma_f32_16x16x32_bf16 v[8:11], v[180:183], v[234:237], v[8:11]
	v_mfma_f32_16x16x32_bf16 v[4:7], v[188:191], v[234:237], v[4:7]
	s_setprio 0
	s_barrier
	s_add_i32 s43, 0, 0x18000
	s_add_i32 s68, 0, 0x1c000
	v_add_u32_e32 v172, s43, v145
	v_add_u32_e32 v188, s68, v145
	ds_read_b128 v[158:161], v172
	ds_read_b128 v[164:167], v172 offset:1024
	ds_read_b128 v[168:171], v172 offset:2048
	ds_read_b128 v[172:175], v172 offset:3072
	ds_read_b128 v[176:179], v188
	ds_read_b128 v[180:183], v188 offset:1024
	ds_read_b128 v[184:187], v188 offset:2048
	ds_read_b128 v[188:191], v188 offset:3072
	s_add_u32 s26, s26, 0x40000
	s_addc_u32 s27, s27, 0
	s_mov_b32 m0, s16
	v_lshl_add_u64 v[200:201], s[26:27], 0, v[150:151]
	ds_read_b128 v[192:195], v163 offset:32768
	ds_read_b128 v[196:199], v163 offset:33792
	ds_read_b128 v[214:217], v163 offset:34816
	ds_read_b128 v[218:221], v163 offset:35840
	ds_read_b128 v[222:225], v163 offset:36864
	ds_read_b128 v[226:229], v163 offset:37888
	ds_read_b128 v[230:233], v163 offset:38912
	ds_read_b128 v[234:237], v163 offset:39936
	global_load_lds_dwordx4 v[200:201], off
	v_lshl_add_u64 v[200:201], s[26:27], 0, v[146:147]
	s_mov_b32 m0, s17
	s_nop 0
	global_load_lds_dwordx4 v[200:201], off
	s_waitcnt vmcnt(8)
	s_waitcnt lgkmcnt(0)
	s_barrier
	s_setprio 1
	s_waitcnt lgkmcnt(0)
	v_mfma_f32_16x16x32_bf16 v[128:131], v[158:161], v[192:195], v[128:131]
	v_mfma_f32_16x16x32_bf16 v[124:127], v[168:171], v[192:195], v[124:127]
	v_mfma_f32_16x16x32_bf16 v[120:123], v[158:161], v[214:217], v[120:123]
	v_mfma_f32_16x16x32_bf16 v[112:115], v[168:171], v[214:217], v[112:115]
	v_mfma_f32_16x16x32_bf16 v[104:107], v[158:161], v[222:225], v[104:107]
	v_mfma_f32_16x16x32_bf16 v[96:99], v[168:171], v[222:225], v[96:99]
	v_mfma_f32_16x16x32_bf16 v[88:91], v[158:161], v[230:233], v[88:91]
	v_mfma_f32_16x16x32_bf16 v[80:83], v[168:171], v[230:233], v[80:83]
	v_mfma_f32_16x16x32_bf16 v[128:131], v[164:167], v[196:199], v[128:131]
	v_mfma_f32_16x16x32_bf16 v[124:127], v[172:175], v[196:199], v[124:127]
	v_mfma_f32_16x16x32_bf16 v[120:123], v[164:167], v[218:221], v[120:123]
	v_mfma_f32_16x16x32_bf16 v[112:115], v[172:175], v[218:221], v[112:115]
	v_mfma_f32_16x16x32_bf16 v[104:107], v[164:167], v[226:229], v[104:107]
	v_mfma_f32_16x16x32_bf16 v[96:99], v[172:175], v[226:229], v[96:99]
	v_mfma_f32_16x16x32_bf16 v[88:91], v[164:167], v[234:237], v[88:91]
	v_mfma_f32_16x16x32_bf16 v[80:83], v[172:175], v[234:237], v[80:83]
	s_setprio 0
	s_setprio 1
	v_mfma_f32_16x16x32_bf16 v[116:119], v[176:179], v[192:195], v[116:119]
	v_mfma_f32_16x16x32_bf16 v[108:111], v[184:187], v[192:195], v[108:111]
	v_mfma_f32_16x16x32_bf16 v[100:103], v[176:179], v[214:217], v[100:103]
	v_mfma_f32_16x16x32_bf16 v[92:95], v[184:187], v[214:217], v[92:95]
	v_mfma_f32_16x16x32_bf16 v[84:87], v[176:179], v[222:225], v[84:87]
	v_mfma_f32_16x16x32_bf16 v[76:79], v[184:187], v[222:225], v[76:79]
	v_mfma_f32_16x16x32_bf16 v[72:75], v[176:179], v[230:233], v[72:75]
	v_mfma_f32_16x16x32_bf16 v[68:71], v[184:187], v[230:233], v[68:71]
	v_mfma_f32_16x16x32_bf16 v[116:119], v[180:183], v[196:199], v[116:119]
	v_mfma_f32_16x16x32_bf16 v[108:111], v[188:191], v[196:199], v[108:111]
	v_mfma_f32_16x16x32_bf16 v[100:103], v[180:183], v[218:221], v[100:103]
	v_mfma_f32_16x16x32_bf16 v[92:95], v[188:191], v[218:221], v[92:95]
	v_mfma_f32_16x16x32_bf16 v[84:87], v[180:183], v[226:229], v[84:87]
	v_mfma_f32_16x16x32_bf16 v[76:79], v[188:191], v[226:229], v[76:79]
	v_mfma_f32_16x16x32_bf16 v[72:75], v[180:183], v[234:237], v[72:75]
	v_mfma_f32_16x16x32_bf16 v[68:71], v[188:191], v[234:237], v[68:71]
	s_setprio 0
	s_barrier
; #define PG8_STAGE(bufoff, gbase, voff) do { _Pragma("unroll") for (int _i = 0; _i < 2; ++_i) \
;         __builtin_amdgcn_global_load_lds((const unsigned*)((const char*)(gbase) + (voff)[_i]), (LAS unsigned*)(lds + (bufoff) + ldsw + _i * 8192), 16, 0, 0); } while (0)
; #define PG8_LDA(dst, b, h) do { _Pragma("unroll") for (int m = 0; m < 4; ++m) _Pragma("unroll") for (int k = 0; k < 2; ++k) dst[m][k] = *(const LAS bf16x8*)(lds + PG8_SA(b, h) + aoff + m * 2048 + k * 1024); } while (0)
; #define PG8_LDB(dst, b, h) do { _Pragma("unroll") for (int n = 0; n < 2; ++n) _Pragma("unroll") for (int k = 0; k < 2; ++k) dst[n][k] = *(const LAS bf16x8*)(lds + PG8_SB(b, h) + boff + n * 2048 + k * 1024); } while (0)
; #define PG8_MMA(ai, bj, At, Bt) do { __builtin_amdgcn_s_setprio(1); _Pragma("unroll") for (int m = 0; m < 4; ++m) _Pragma("unroll") for (int n = 0; n < 2; ++n) _Pragma("unroll") for (int k = 0; k < 2; ++k) \
;         acc[ai][bj][m][n] = __builtin_amdgcn_mfma_f32_16x16x32_bf16(Bt[n][k], At[m][k], acc[ai][bj][m][n], 0, 0, 0); __builtin_amdgcn_s_setprio(0); } while (0)
; #define PG8_WAIT_V(n) asm volatile("s_waitcnt vmcnt(" #n ")" ::: "memory")
; #define PG8_WAIT_L(n) asm volatile("s_waitcnt lgkmcnt(" #n ")" ::: "memory")
; #define PG8_BAR __builtin_amdgcn_s_barrier()
;     __device__ __forceinline__ void operator()(const f32x4 (&acc)[2][2][4][2], const Unit& u, int wr, int wc, int fr, int fq) const {
;         if (u.pn < 11) {
; template <class Epi>
; __device__ __forceinline__ void gemm_phase(LAS unsigned char* lds, const Gemm g, const int G, const int cidx, const Epi& E) {
;     ...
;             PG8_WAIT_V(8); PG8_WAIT_L(0); PG8_BAR; PG8_MMA(1, 0, At, B0); PG8_MMA(1, 1, At, B1); PG8_BAR; PG8_SCHED;
;             PG8_LDB(B0, 1, 0); PG8_LDB(B1, 1, 1); PG8_SCHED; PG8_LDA(At, 1, 0); PG8_STAGE(PG8_SA(0, 1), a2 + hstep, voffA);
;             PG8_WAIT_V(8); PG8_WAIT_L(0); PG8_BAR; PG8_MMA(0, 0, At, B0); PG8_MMA(0, 1, At, B1); PG8_BAR; PG8_SCHED;
;             PG8_LDA(At, 1, 1); PG8_STAGE(PG8_SB(1, 0), b3, voffB); PG8_STAGE(PG8_SB(1, 1), b3 + hstep, voffB); PG8_STAGE(PG8_SA(1, 0), a3, voffA);
;             PG8_WAIT_V(8); PG8_WAIT_L(0); PG8_BAR; PG8_MMA(1, 0, At, B0); PG8_MMA(1, 1, At, B1); PG8_BAR; PG8_SCHED;
;         }
;         if constexpr (!Epi::AFTER_DRAIN) E(acc, cur, wr, wc, fr, fq);
;         if (!has_next) break;
	s_add_i32 s26, s43, s95
	v_lshl_add_u64 v[132:133], v[132:133], 0, s[46:47]
	s_mov_b32 m0, s26
	ds_read_b128 v[192:195], v163 offset:49152
	ds_read_b128 v[196:199], v163 offset:50176
	ds_read_b128 v[214:217], v163 offset:51200
	ds_read_b128 v[218:221], v163 offset:52224
	ds_read_b128 v[222:225], v163 offset:53248
	ds_read_b128 v[226:229], v163 offset:54272
	ds_read_b128 v[230:233], v163 offset:55296
	ds_read_b128 v[234:237], v163 offset:56320
	global_load_lds_dwordx4 v[132:133], off
	s_add_i32 m0, s26, 0x2000
	s_add_u32 s24, s24, 0x40080
	v_lshl_add_u64 v[132:133], v[134:135], 0, s[46:47]
	s_addc_u32 s25, s25, 0
	s_add_i32 s26, s68, s95
	global_load_lds_dwordx4 v[132:133], off
	v_lshl_add_u64 v[132:133], s[24:25], 0, v[148:149]
	s_mov_b32 m0, s26
	s_nop 0
	global_load_lds_dwordx4 v[132:133], off
	v_lshl_add_u64 v[132:133], s[24:25], 0, v[0:1]
	s_add_i32 m0, s26, 0x2000
	s_nop 0
	global_load_lds_dwordx4 v[132:133], off
	v_lshl_add_u64 v[132:133], v[140:141], 0, s[46:47]
	s_mov_b32 m0, s84
	s_nop 0
	global_load_lds_dwordx4 v[132:133], off
	v_lshl_add_u64 v[132:133], v[142:143], 0, s[46:47]
	s_mov_b32 m0, s76
	s_nop 0
	global_load_lds_dwordx4 v[132:133], off
	s_waitcnt vmcnt(8)
	s_waitcnt lgkmcnt(0)
	s_barrier
	s_setprio 1
	s_waitcnt lgkmcnt(0)
	v_mfma_f32_16x16x32_bf16 v[64:67], v[158:161], v[192:195], v[64:67]
	v_mfma_f32_16x16x32_bf16 v[60:63], v[168:171], v[192:195], v[60:63]
	v_mfma_f32_16x16x32_bf16 v[56:59], v[158:161], v[214:217], v[56:59]
	v_mfma_f32_16x16x32_bf16 v[48:51], v[168:171], v[214:217], v[48:51]
	v_mfma_f32_16x16x32_bf16 v[40:43], v[158:161], v[222:225], v[40:43]
	v_mfma_f32_16x16x32_bf16 v[32:35], v[168:171], v[222:225], v[32:35]
	v_mfma_f32_16x16x32_bf16 v[24:27], v[158:161], v[230:233], v[24:27]
	v_mfma_f32_16x16x32_bf16 v[16:19], v[168:171], v[230:233], v[16:19]
	v_mfma_f32_16x16x32_bf16 v[64:67], v[164:167], v[196:199], v[64:67]
	v_mfma_f32_16x16x32_bf16 v[60:63], v[172:175], v[196:199], v[60:63]
	v_mfma_f32_16x16x32_bf16 v[56:59], v[164:167], v[218:221], v[56:59]
	v_mfma_f32_16x16x32_bf16 v[48:51], v[172:175], v[218:221], v[48:51]
	v_mfma_f32_16x16x32_bf16 v[40:43], v[164:167], v[226:229], v[40:43]
	v_mfma_f32_16x16x32_bf16 v[32:35], v[172:175], v[226:229], v[32:35]
	v_mfma_f32_16x16x32_bf16 v[24:27], v[164:167], v[234:237], v[24:27]
	v_mfma_f32_16x16x32_bf16 v[16:19], v[172:175], v[234:237], v[16:19]
	s_setprio 0
	s_setprio 1
	v_mfma_f32_16x16x32_bf16 v[52:55], v[176:179], v[192:195], v[52:55]
	v_mfma_f32_16x16x32_bf16 v[44:47], v[184:187], v[192:195], v[44:47]
	v_mfma_f32_16x16x32_bf16 v[36:39], v[176:179], v[214:217], v[36:39]
	v_mfma_f32_16x16x32_bf16 v[28:31], v[184:187], v[214:217], v[28:31]
	v_mfma_f32_16x16x32_bf16 v[20:23], v[176:179], v[222:225], v[20:23]
	v_mfma_f32_16x16x32_bf16 v[12:15], v[184:187], v[222:225], v[12:15]
	v_mfma_f32_16x16x32_bf16 v[8:11], v[176:179], v[230:233], v[8:11]
	v_mfma_f32_16x16x32_bf16 v[4:7], v[184:187], v[230:233], v[4:7]
	v_mfma_f32_16x16x32_bf16 v[52:55], v[180:183], v[196:199], v[52:55]
	v_mfma_f32_16x16x32_bf16 v[44:47], v[188:191], v[196:199], v[44:47]
	v_mfma_f32_16x16x32_bf16 v[36:39], v[180:183], v[218:221], v[36:39]
	v_mfma_f32_16x16x32_bf16 v[28:31], v[188:191], v[218:221], v[28:31]
	v_mfma_f32_16x16x32_bf16 v[20:23], v[180:183], v[226:229], v[20:23]
	v_mfma_f32_16x16x32_bf16 v[12:15], v[188:191], v[226:229], v[12:15]
	v_mfma_f32_16x16x32_bf16 v[8:11], v[180:183], v[234:237], v[8:11]
	v_mfma_f32_16x16x32_bf16 v[4:7], v[188:191], v[234:237], v[4:7]
	s_add_i32 s45, s45, 2
	s_add_u32 s42, s42, 0x100
	s_addc_u32 s44, s44, 0
	s_add_u32 s20, s20, 0x100
	s_addc_u32 s21, s21, 0
	s_cmp_gt_u32 s45, 13
	s_setprio 0
	s_barrier
	s_cbranch_scc0 .LBB0_601
	s_cmp_gt_i32 s35, 10
	s_mov_b64 s[20:21], -1
	s_mov_b32 s26, 0x1a000
	s_mov_b32 s27, 0x19000
	s_cbranch_scc0 .LBB0_604
; __device__ __forceinline__ unsigned pk2(float lo, float hi) { unsigned r; asm("v_cvt_pk_bf16_f32 %0, %1, %2" : "=v"(r) : "v"(lo), "v"(hi)); return r; }
;     __device__ __forceinline__ void operator()(const f32x4 (&acc)[2][2][4][2], const Unit& u, int wr, int wc, int fr, int fq) const {
;     ...
;             const int g = u.pn - 11, n = g >> 2, q = g & 3;
;             bf16_t* blk = Gt + (((size_t)n * 64 + u.pm) * 8 + q * 2) * 32768 + (size_t)((wr * 4 * 4 + wc) * 64 + fq * 16 + fr) * 8;
; #pragma unroll
;             for (int ai = 0; ai < 2; ++ai)
; #pragma unroll
;                 for (int m = 0; m < 4; ++m)
; #pragma unroll
;                     for (int bj = 0; bj < 2; ++bj) { const f32x4 v0 = acc[ai][bj][m][0], v1 = acc[ai][bj][m][1];
;                         u32x4 w; w.x = pk2(v0[0], v0[1]); w.y = pk2(v0[2], v0[3]); w.z = pk2(v1[0], v1[1]); w.w = pk2(v1[2], v1[3]);
;                         *(u32x4*)(blk + (size_t)bj * 32768 + (size_t)((ai * 8 + m) * 4) * 512) = w; }
	s_add_i32 s9, s35, -11
	s_mov_b32 s21, s77
	s_lshr_b32 s20, s9, 2
	s_ashr_i32 s19, s18, 31
	s_lshl_b64 s[20:21], s[20:21], 9
	s_lshl_b64 s[24:25], s[18:19], 3
	s_add_u32 s11, s20, s24
	s_addc_u32 s21, s21, s25
	s_lshl_b32 s9, s9, 1
	s_and_b32 s9, s9, 6
	s_or_b32 s20, s11, s9
	s_lshl_b64 s[20:21], s[20:21], 16
	v_lshl_add_u64 v[158:159], v[152:153], 0, s[20:21]
	s_mov_b32 s9, 0x11000
	v_add_co_u32_e32 v132, vcc, s9, v158
	v_cvt_pk_bf16_f32 v164, v128, v129
	v_cvt_pk_bf16_f32 v165, v130, v131
	v_cvt_pk_bf16_f32 v166, v124, v125
	v_cvt_pk_bf16_f32 v167, v126, v127
	s_nop 1
	v_addc_co_u32_e32 v133, vcc, 0, v159, vcc
	global_store_dwordx4 v[158:159], v[164:167], off
	v_add_co_u32_e32 v134, vcc, s81, v158
	s_nop 0
	v_cvt_pk_bf16_f32 v164, v116, v117
	v_cvt_pk_bf16_f32 v165, v118, v119
	v_cvt_pk_bf16_f32 v166, v108, v109
	v_cvt_pk_bf16_f32 v167, v110, v111
	global_store_dwordx4 v[132:133], v[164:167], off offset:-4096
	v_addc_co_u32_e32 v135, vcc, 0, v159, vcc
	s_nop 0
	v_cvt_pk_bf16_f32 v164, v120, v121
	v_cvt_pk_bf16_f32 v165, v122, v123
	v_cvt_pk_bf16_f32 v166, v112, v113
	v_cvt_pk_bf16_f32 v167, v114, v115
	s_mov_b32 s9, 0x13000
	global_store_dwordx4 v[134:135], v[164:167], off offset:-4096
	s_mov_b64 s[20:21], 0
	s_nop 0
	v_cvt_pk_bf16_f32 v164, v100, v101
	v_cvt_pk_bf16_f32 v165, v102, v103
	v_cvt_pk_bf16_f32 v166, v92, v93
	v_cvt_pk_bf16_f32 v167, v94, v95
	global_store_dwordx4 v[132:133], v[164:167], off
	v_add_co_u32_e32 v132, vcc, s9, v158
	s_nop 0
	v_cvt_pk_bf16_f32 v164, v104, v105
	v_cvt_pk_bf16_f32 v165, v106, v107
	v_cvt_pk_bf16_f32 v166, v96, v97
	v_cvt_pk_bf16_f32 v167, v98, v99
	s_nop 0
	v_addc_co_u32_e32 v133, vcc, 0, v159, vcc
	global_store_dwordx4 v[134:135], v[164:167], off
	v_add_co_u32_e32 v134, vcc, s82, v158
	s_nop 0
	v_cvt_pk_bf16_f32 v164, v84, v85
	v_cvt_pk_bf16_f32 v165, v86, v87
	v_cvt_pk_bf16_f32 v166, v76, v77
	v_cvt_pk_bf16_f32 v167, v78, v79
	global_store_dwordx4 v[132:133], v[164:167], off offset:-4096
	v_addc_co_u32_e32 v135, vcc, 0, v159, vcc
	s_nop 0
	v_cvt_pk_bf16_f32 v164, v88, v89
	v_cvt_pk_bf16_f32 v165, v90, v91
	v_cvt_pk_bf16_f32 v166, v80, v81
	v_cvt_pk_bf16_f32 v167, v82, v83
	s_mov_b32 s9, 0x9000
	global_store_dwordx4 v[134:135], v[164:167], off
	s_nop 1
	v_cvt_pk_bf16_f32 v164, v72, v73
	v_cvt_pk_bf16_f32 v165, v74, v75
	v_cvt_pk_bf16_f32 v166, v68, v69
	v_cvt_pk_bf16_f32 v167, v70, v71
	global_store_dwordx4 v[132:133], v[164:167], off
	v_add_co_u32_e32 v132, vcc, s9, v158
	s_nop 0
	v_cvt_pk_bf16_f32 v164, v64, v65
	v_cvt_pk_bf16_f32 v165, v66, v67
	v_cvt_pk_bf16_f32 v166, v60, v61
	v_cvt_pk_bf16_f32 v167, v62, v63
	s_nop 0
	v_addc_co_u32_e32 v133, vcc, 0, v159, vcc
	v_add_co_u32_e32 v134, vcc, s27, v158
	global_store_dwordx4 v[132:133], v[164:167], off offset:-4096
	s_nop 0
	v_addc_co_u32_e32 v135, vcc, 0, v159, vcc
	v_cvt_pk_bf16_f32 v164, v52, v53
	v_cvt_pk_bf16_f32 v165, v54, v55
	v_cvt_pk_bf16_f32 v166, v44, v45
	v_cvt_pk_bf16_f32 v167, v46, v47
	s_mov_b32 s9, 0xb000
	global_store_dwordx4 v[134:135], v[164:167], off offset:-4096
	s_nop 1
	v_cvt_pk_bf16_f32 v164, v56, v57
	v_cvt_pk_bf16_f32 v165, v58, v59
	v_cvt_pk_bf16_f32 v166, v48, v49
	v_cvt_pk_bf16_f32 v167, v50, v51
	global_store_dwordx4 v[132:133], v[164:167], off
	v_add_co_u32_e32 v132, vcc, s9, v158
	s_nop 0
	v_cvt_pk_bf16_f32 v164, v36, v37
	v_cvt_pk_bf16_f32 v165, v38, v39
	v_cvt_pk_bf16_f32 v166, v28, v29
	v_cvt_pk_bf16_f32 v167, v30, v31
	s_nop 0
	v_addc_co_u32_e32 v133, vcc, 0, v159, vcc
	global_store_dwordx4 v[134:135], v[164:167], off
	v_add_co_u32_e32 v134, vcc, s26, v158
	s_nop 0
	v_cvt_pk_bf16_f32 v164, v40, v41
	v_cvt_pk_bf16_f32 v165, v42, v43
	v_cvt_pk_bf16_f32 v166, v32, v33
	v_cvt_pk_bf16_f32 v167, v34, v35
	global_store_dwordx4 v[132:133], v[164:167], off offset:-4096
	v_addc_co_u32_e32 v135, vcc, 0, v159, vcc
	s_nop 0
	v_cvt_pk_bf16_f32 v164, v20, v21
	v_cvt_pk_bf16_f32 v165, v22, v23
	v_cvt_pk_bf16_f32 v166, v12, v13
	v_cvt_pk_bf16_f32 v167, v14, v15
	global_store_dwordx4 v[134:135], v[164:167], off
	s_nop 1
	v_cvt_pk_bf16_f32 v164, v24, v25
	v_cvt_pk_bf16_f32 v165, v26, v27
	v_cvt_pk_bf16_f32 v166, v16, v17
	v_cvt_pk_bf16_f32 v167, v18, v19
	global_store_dwordx4 v[132:133], v[164:167], off
	v_add_co_u32_e32 v132, vcc, 0x1b000, v158
	s_nop 0
	v_cvt_pk_bf16_f32 v164, v8, v9
	v_cvt_pk_bf16_f32 v165, v10, v11
	v_cvt_pk_bf16_f32 v166, v4, v5
	v_cvt_pk_bf16_f32 v167, v6, v7
	s_nop 0
	v_addc_co_u32_e32 v133, vcc, 0, v159, vcc
	global_store_dwordx4 v[132:133], v[164:167], off
